# plus: gelu sign-select and abs folded into VOP3 modifiers (one fma per element), gate-up epilogue log2e folded into rstd and shifts, dead rsqrt denormal rescue dropped
# speedup vs baseline: 1.0244x; 1.0025x over previous
.LBB0_86:
	s_lshl_b32 s2, s62, 8
	s_add_i32 s2, s2, s17
	v_add_u32_e32 v160, s2, v171
	s_and_b64 s[2:3], s[38:39], exec
	s_mov_b32 s2, 0x7800000
	s_cselect_b32 s2, s2, 0xa800000
	s_add_u32 s2, s72, s2
	s_addc_u32 s3, s73, 0
	s_and_b64 s[4:5], s[38:39], exec
	s_movk_i32 s4, 0x800
	s_cselect_b32 s4, s4, 0x3000
	s_or_b32 s5, s30, 0x800
	s_and_b64 s[6:7], s[38:39], exec
	s_cselect_b32 s5, 0, s5
	v_add_u32_e32 v158, s5, v160
	v_ashrrev_i32_e32 v159, 31, v158
	v_lshl_add_u64 v[158:159], v[158:159], 2, s[0:1]
	global_load_dword v161, v[158:159], off
	global_load_dword v185, v[158:159], off offset:64
	global_load_dword v183, v[158:159], off offset:128
	global_load_dword v181, v[158:159], off offset:192
	global_load_dword v179, v[158:159], off offset:512
	global_load_dword v177, v[158:159], off offset:576
	global_load_dword v175, v[158:159], off offset:640
	global_load_dword v173, v[158:159], off offset:704
	v_add_u32_e32 v184, 16, v160
	v_add_u32_e32 v182, 32, v160
	v_add_u32_e32 v180, 48, v160
	v_add_u32_e32 v178, 0x80, v160
	v_add_u32_e32 v176, 0x90, v160
	v_add_u32_e32 v174, 0xa0, v160
	v_add_u32_e32 v172, 0xb0, v160
	v_lshl_add_u64 v[158:159], v[156:157], 1, s[2:3]
	s_mov_b32 s2, 0x3e6d3388
	s_mov_b32 s6, 0x3f07dc22
	s_mov_b32 s62, 0xbf38aa3b
	s_mov_b32 s26, 0x3f35f0e3
	s_mov_b32 s30, 0xbe11a98e
	s_mov_b32 s40, 0x3e027906
	s_waitcnt vmcnt(0)
	v_fmamk_f32 v162, v161, 0x3a800000, v202
	v_cmp_gt_f32_e32 vcc, s68, v162
	v_mul_f32_e32 v163, 0x4b800000, v162
	s_nop 0
	v_cndmask_b32_e32 v162, v162, v163, vcc
	v_rsq_f32_e32 v162, v162
	s_nop 0
	v_mul_f32_e32 v163, 0x45800000, v162
	v_cndmask_b32_e32 v162, v162, v163, vcc
	v_cndmask_b32_e64 v164, v161, v162, s[38:39]
	v_mad_i64_i32 v[160:161], s[0:1], s4, v160, 0
	v_lshl_add_u64 v[162:163], v[160:161], 1, v[158:159]
	v_pk_fma_f32 v[160:161], v[142:143], v[34:35], v[164:165] op_sel_hi:[1,1,0]
	v_pk_fma_f32 v[166:167], v[144:145], v[36:37], v[164:165] op_sel_hi:[1,1,0]
	v_pk_fma_f32 v[186:187], v[142:143], v[164:165], v[34:35] op_sel_hi:[1,0,1]
	v_pk_fma_f32 v[142:143], v[144:145], v[164:165], v[36:37] op_sel_hi:[1,0,1]
	v_pk_fma_f32 v[144:145], v[138:139], v[42:43], v[164:165] op_sel_hi:[1,1,0]
	v_cndmask_b32_e64 v143, v167, v143, s[38:39]
	v_cndmask_b32_e64 v142, v166, v142, s[38:39]
	v_cndmask_b32_e64 v166, v160, v186, s[38:39]
	v_cndmask_b32_e64 v167, v161, v187, s[38:39]
	v_pk_fma_f32 v[138:139], v[138:139], v[164:165], v[42:43] op_sel_hi:[1,0,1]
	v_pk_fma_f32 v[160:161], v[140:141], v[44:45], v[164:165] op_sel_hi:[1,1,0]
	v_cndmask_b32_e64 v144, v144, v138, s[38:39]
	v_cndmask_b32_e64 v145, v145, v139, s[38:39]
	v_pk_fma_f32 v[140:141], v[140:141], v[164:165], v[44:45] op_sel_hi:[1,0,1]
	v_fma_f32 v138, |v166|, s2, 1.0
	v_fma_f32 v139, |v167|, s2, 1.0
	v_cndmask_b32_e64 v161, v161, v141, s[38:39]
	v_cndmask_b32_e64 v160, v160, v140, s[38:39]
	v_rcp_f32_e32 v140, v138
	v_rcp_f32_e32 v141, v139
	s_mov_b32 s0, 0xbf3a00e3
	v_mov_b64_e32 v[138:139], s[0:1]
	v_pk_mul_f32 v[188:189], v[166:167], v[166:167]
	v_pk_fma_f32 v[186:187], v[140:141], s[6:7], v[138:139] op_sel_hi:[1,0,0]
	v_pk_mul_f32 v[188:189], v[188:189], s[62:63] op_sel_hi:[1,0]
	v_pk_fma_f32 v[186:187], v[140:141], v[186:187], s[26:27] op_sel_hi:[1,1,0]
	v_exp_f32_e32 v188, v188
	v_exp_f32_e32 v189, v189
	v_pk_fma_f32 v[186:187], v[140:141], v[186:187], s[30:31] op_sel_hi:[1,1,0]
	v_pk_fma_f32 v[186:187], v[140:141], v[186:187], s[40:41] op_sel_hi:[1,1,0]
	s_nop 0
	v_pk_mul_f32 v[140:141], v[140:141], v[186:187]
	v_pk_mul_f32 v[186:187], v[142:143], v[142:143]
	v_pk_mul_f32 v[140:141], v[188:189], v[140:141]
	v_pk_mul_f32 v[186:187], v[186:187], s[62:63] op_sel_hi:[1,0]
	v_max_f32_e32 v188, 0, v166
	v_max_f32_e32 v189, 0, v167
	v_fma_f32 v140, -|v166|, v140, v188
	v_fma_f32 v141, -|v167|, v141, v189
	v_fma_f32 v166, |v142|, s2, 1.0
	v_fma_f32 v167, |v143|, s2, 1.0
	v_rcp_f32_e32 v166, v166
	v_rcp_f32_e32 v167, v167
	v_exp_f32_e32 v186, v186
	v_exp_f32_e32 v187, v187
	v_pk_fma_f32 v[188:189], v[166:167], s[6:7], v[138:139] op_sel_hi:[1,0,0]
	s_nop 0
	v_pk_fma_f32 v[188:189], v[166:167], v[188:189], s[26:27] op_sel_hi:[1,1,0]
	s_nop 0
	v_pk_fma_f32 v[188:189], v[166:167], v[188:189], s[30:31] op_sel_hi:[1,1,0]
	s_nop 0
	v_pk_fma_f32 v[188:189], v[166:167], v[188:189], s[40:41] op_sel_hi:[1,1,0]
	s_nop 0
	v_pk_mul_f32 v[166:167], v[166:167], v[188:189]
	v_pk_mul_f32 v[188:189], v[144:145], v[144:145]
	v_pk_mul_f32 v[166:167], v[186:187], v[166:167]
	v_pk_mul_f32 v[188:189], v[188:189], s[62:63] op_sel_hi:[1,0]
	v_max_f32_e32 v186, 0, v142
	v_max_f32_e32 v187, 0, v143
	v_fma_f32 v166, -|v142|, v166, v186
	v_fma_f32 v167, -|v143|, v167, v187
	v_exp_f32_e32 v188, v188
	v_mov_b32_e32 v142, v166
	v_exp_f32_e32 v189, v189
	v_mov_b32_e32 v143, v167
	v_fma_f32 v166, |v144|, s2, 1.0
	v_fma_f32 v167, |v145|, s2, 1.0
	v_rcp_f32_e32 v166, v166
	v_rcp_f32_e32 v167, v167
	s_nop 0
	v_pk_fma_f32 v[186:187], v[166:167], s[6:7], v[138:139] op_sel_hi:[1,0,0]
	s_nop 0
	v_pk_fma_f32 v[186:187], v[166:167], v[186:187], s[26:27] op_sel_hi:[1,1,0]
	s_nop 0
	v_pk_fma_f32 v[186:187], v[166:167], v[186:187], s[30:31] op_sel_hi:[1,1,0]
	s_nop 0
	v_pk_fma_f32 v[186:187], v[166:167], v[186:187], s[40:41] op_sel_hi:[1,1,0]
	s_nop 0
	v_pk_mul_f32 v[166:167], v[166:167], v[186:187]
	v_pk_mul_f32 v[186:187], v[160:161], v[160:161]
	v_pk_mul_f32 v[166:167], v[188:189], v[166:167]
	v_pk_mul_f32 v[186:187], v[186:187], s[62:63] op_sel_hi:[1,0]
	v_max_f32_e32 v188, 0, v144
	v_max_f32_e32 v189, 0, v145
	v_fma_f32 v166, -|v144|, v166, v188
	v_fma_f32 v167, -|v145|, v167, v189
	v_exp_f32_e32 v186, v186
	v_mov_b32_e32 v144, v166
	v_exp_f32_e32 v187, v187
	v_mov_b32_e32 v145, v167
	v_fma_f32 v166, |v160|, s2, 1.0
	v_fma_f32 v167, |v161|, s2, 1.0
	v_rcp_f32_e32 v166, v166
	v_rcp_f32_e32 v167, v167
	s_nop 0
	v_pk_fma_f32 v[188:189], v[166:167], s[6:7], v[138:139] op_sel_hi:[1,0,0]
	s_nop 0
	v_pk_fma_f32 v[188:189], v[166:167], v[188:189], s[26:27] op_sel_hi:[1,1,0]
	s_nop 0
	v_pk_fma_f32 v[188:189], v[166:167], v[188:189], s[30:31] op_sel_hi:[1,1,0]
	s_nop 0
	v_pk_fma_f32 v[188:189], v[166:167], v[188:189], s[40:41] op_sel_hi:[1,1,0]
	s_nop 0
	v_pk_mul_f32 v[166:167], v[166:167], v[188:189]
	v_cvt_pk_bf16_f32 v188, v144, v145
	v_pk_mul_f32 v[166:167], v[186:187], v[166:167]
	s_nop 0
	v_max_f32_e32 v186, 0, v160
	v_max_f32_e32 v187, 0, v161
	v_fma_f32 v166, -|v160|, v166, v186
	v_fma_f32 v167, -|v161|, v167, v187
	s_nop 0
	v_mov_b32_e32 v160, v166
	v_cvt_pk_bf16_f32 v186, v140, v141
	s_nop 0
	v_mov_b32_e32 v161, v167
	v_pk_fma_f32 v[166:167], v[134:135], v[38:39], v[164:165] op_sel_hi:[1,1,0]
	v_pk_fma_f32 v[134:135], v[134:135], v[164:165], v[38:39] op_sel_hi:[1,0,1]
	v_cvt_pk_bf16_f32 v187, v142, v143
	v_cndmask_b32_e64 v134, v166, v134, s[38:39]
	v_cndmask_b32_e64 v135, v167, v135, s[38:39]
	v_pk_fma_f32 v[166:167], v[130:131], v[46:47], v[164:165] op_sel_hi:[1,1,0]
	v_pk_fma_f32 v[130:131], v[130:131], v[164:165], v[46:47] op_sel_hi:[1,0,1]
	v_cvt_pk_bf16_f32 v189, v160, v161
	v_cndmask_b32_e64 v166, v166, v130, s[38:39]
	v_cndmask_b32_e64 v167, v167, v131, s[38:39]
	v_fma_f32 v130, |v134|, s2, 1.0
	v_fma_f32 v131, |v135|, s2, 1.0
	global_store_dwordx4 v[162:163], v[186:189], off
	v_rcp_f32_e32 v130, v130
	v_rcp_f32_e32 v131, v131
	v_pk_fma_f32 v[186:187], v[136:137], v[40:41], v[164:165] op_sel_hi:[1,1,0]
	v_pk_fma_f32 v[136:137], v[136:137], v[164:165], v[40:41] op_sel_hi:[1,0,1]
	v_pk_mul_f32 v[188:189], v[134:135], v[134:135]
	v_cndmask_b32_e64 v187, v187, v137, s[38:39]
	v_cndmask_b32_e64 v186, v186, v136, s[38:39]
	v_pk_fma_f32 v[136:137], v[132:133], v[48:49], v[164:165] op_sel_hi:[1,1,0]
	v_pk_fma_f32 v[132:133], v[132:133], v[164:165], v[48:49] op_sel_hi:[1,0,1]
	v_pk_mul_f32 v[188:189], v[188:189], s[62:63] op_sel_hi:[1,0]
	v_cndmask_b32_e64 v137, v137, v133, s[38:39]
	v_cndmask_b32_e64 v136, v136, v132, s[38:39]
	v_pk_fma_f32 v[132:133], v[130:131], s[6:7], v[138:139] op_sel_hi:[1,0,0]
	v_exp_f32_e32 v188, v188
	v_pk_fma_f32 v[132:133], v[130:131], v[132:133], s[26:27] op_sel_hi:[1,1,0]
	v_exp_f32_e32 v189, v189
	v_pk_fma_f32 v[132:133], v[130:131], v[132:133], s[30:31] op_sel_hi:[1,1,0]
	v_pk_fma_f32 v[132:133], v[130:131], v[132:133], s[40:41] op_sel_hi:[1,1,0]
	s_nop 0
	v_pk_mul_f32 v[130:131], v[130:131], v[132:133]
	v_pk_mul_f32 v[132:133], v[186:187], v[186:187]
	v_pk_mul_f32 v[130:131], v[188:189], v[130:131]
	v_pk_mul_f32 v[132:133], v[132:133], s[62:63] op_sel_hi:[1,0]
	v_max_f32_e32 v188, 0, v134
	v_max_f32_e32 v189, 0, v135
	v_fma_f32 v130, -|v134|, v130, v188
	v_fma_f32 v131, -|v135|, v131, v189
	v_fma_f32 v134, |v186|, s2, 1.0
	v_fma_f32 v135, |v187|, s2, 1.0
	v_rcp_f32_e32 v134, v134
	v_rcp_f32_e32 v135, v135
	v_exp_f32_e32 v132, v132
	v_exp_f32_e32 v133, v133
	v_pk_fma_f32 v[188:189], v[134:135], s[6:7], v[138:139] op_sel_hi:[1,0,0]
	s_nop 0
	v_pk_fma_f32 v[188:189], v[134:135], v[188:189], s[26:27] op_sel_hi:[1,1,0]
	s_nop 0
	v_pk_fma_f32 v[188:189], v[134:135], v[188:189], s[30:31] op_sel_hi:[1,1,0]
	s_nop 0
	v_pk_fma_f32 v[188:189], v[134:135], v[188:189], s[40:41] op_sel_hi:[1,1,0]
	s_nop 0
	v_pk_mul_f32 v[134:135], v[134:135], v[188:189]
	v_pk_mul_f32 v[188:189], v[166:167], v[166:167]
	v_pk_mul_f32 v[132:133], v[132:133], v[134:135]
	v_pk_mul_f32 v[188:189], v[188:189], s[62:63] op_sel_hi:[1,0]
	v_max_f32_e32 v134, 0, v186
	v_max_f32_e32 v135, 0, v187
	v_fma_f32 v132, -|v186|, v132, v134
	v_fma_f32 v133, -|v187|, v133, v135
	v_exp_f32_e32 v188, v188
	v_exp_f32_e32 v189, v189
	v_fma_f32 v134, |v166|, s2, 1.0
	v_fma_f32 v135, |v167|, s2, 1.0
	v_rcp_f32_e32 v134, v134
	v_rcp_f32_e32 v135, v135
	s_nop 0
	v_pk_fma_f32 v[186:187], v[134:135], s[6:7], v[138:139] op_sel_hi:[1,0,0]
	s_nop 0
	v_pk_fma_f32 v[186:187], v[134:135], v[186:187], s[26:27] op_sel_hi:[1,1,0]
	s_nop 0
	v_pk_fma_f32 v[186:187], v[134:135], v[186:187], s[30:31] op_sel_hi:[1,1,0]
	s_nop 0
	v_pk_fma_f32 v[186:187], v[134:135], v[186:187], s[40:41] op_sel_hi:[1,1,0]
	s_nop 0
	v_pk_mul_f32 v[134:135], v[134:135], v[186:187]
	v_pk_mul_f32 v[186:187], v[136:137], v[136:137]
	v_pk_mul_f32 v[134:135], v[188:189], v[134:135]
	v_pk_mul_f32 v[186:187], v[186:187], s[62:63] op_sel_hi:[1,0]
	v_max_f32_e32 v188, 0, v166
	v_max_f32_e32 v189, 0, v167
	v_fma_f32 v134, -|v166|, v134, v188
	v_fma_f32 v135, -|v167|, v135, v189
	v_fma_f32 v166, |v136|, s2, 1.0
	v_fma_f32 v167, |v137|, s2, 1.0
	v_rcp_f32_e32 v166, v166
	v_rcp_f32_e32 v167, v167
	v_exp_f32_e32 v186, v186
	v_exp_f32_e32 v187, v187
	v_pk_fma_f32 v[188:189], v[166:167], s[6:7], v[138:139] op_sel_hi:[1,0,0]
	s_nop 0
	v_pk_fma_f32 v[188:189], v[166:167], v[188:189], s[26:27] op_sel_hi:[1,1,0]
	s_nop 0
	v_pk_fma_f32 v[188:189], v[166:167], v[188:189], s[30:31] op_sel_hi:[1,1,0]
	s_nop 0
	v_pk_fma_f32 v[188:189], v[166:167], v[188:189], s[40:41] op_sel_hi:[1,1,0]
	s_nop 0
	v_pk_mul_f32 v[166:167], v[166:167], v[188:189]
	v_cvt_pk_bf16_f32 v188, v134, v135
	v_pk_mul_f32 v[166:167], v[186:187], v[166:167]
	s_nop 0
	v_max_f32_e32 v186, 0, v136
	v_max_f32_e32 v187, 0, v137
	v_fma_f32 v166, -|v136|, v166, v186
	v_fma_f32 v167, -|v137|, v167, v187
	s_nop 0
	v_mov_b32_e32 v136, v166
	v_cvt_pk_bf16_f32 v186, v130, v131
	s_nop 0
	v_mov_b32_e32 v137, v167
	v_cvt_pk_bf16_f32 v187, v132, v133
	v_cvt_pk_bf16_f32 v189, v136, v137
	global_store_dwordx4 v[162:163], v[186:189], off offset:256
	v_fmamk_f32 v162, v185, 0x3a800000, v202
	v_cmp_gt_f32_e32 vcc, s68, v162
	v_mul_f32_e32 v163, 0x4b800000, v162
	s_nop 0
	v_cndmask_b32_e32 v162, v162, v163, vcc
	v_rsq_f32_e32 v162, v162
	s_nop 0
	v_mul_f32_e32 v163, 0x45800000, v162
	v_cndmask_b32_e32 v162, v162, v163, vcc
	v_cndmask_b32_e64 v164, v185, v162, s[38:39]
	v_pk_fma_f32 v[166:167], v[126:127], v[34:35], v[164:165] op_sel_hi:[1,1,0]
	v_pk_fma_f32 v[126:127], v[126:127], v[164:165], v[34:35] op_sel_hi:[1,0,1]
	v_mad_i64_i32 v[162:163], s[0:1], s4, v184, 0
	v_cndmask_b32_e64 v126, v166, v126, s[38:39]
	v_cndmask_b32_e64 v127, v167, v127, s[38:39]
	v_pk_fma_f32 v[166:167], v[122:123], v[42:43], v[164:165] op_sel_hi:[1,1,0]
	v_pk_fma_f32 v[122:123], v[122:123], v[164:165], v[42:43] op_sel_hi:[1,0,1]
	v_pk_fma_f32 v[184:185], v[128:129], v[36:37], v[164:165] op_sel_hi:[1,1,0]
	v_cndmask_b32_e64 v166, v166, v122, s[38:39]
	v_cndmask_b32_e64 v167, v167, v123, s[38:39]
	v_fma_f32 v122, |v126|, s2, 1.0
	v_fma_f32 v123, |v127|, s2, 1.0
	v_pk_fma_f32 v[128:129], v[128:129], v[164:165], v[36:37] op_sel_hi:[1,0,1]
	v_rcp_f32_e32 v122, v122
	v_rcp_f32_e32 v123, v123
	v_cndmask_b32_e64 v185, v185, v129, s[38:39]
	v_cndmask_b32_e64 v184, v184, v128, s[38:39]
	v_pk_fma_f32 v[128:129], v[124:125], v[44:45], v[164:165] op_sel_hi:[1,1,0]
	v_pk_fma_f32 v[124:125], v[124:125], v[164:165], v[44:45] op_sel_hi:[1,0,1]
	v_pk_mul_f32 v[186:187], v[126:127], v[126:127]
	v_cndmask_b32_e64 v129, v129, v125, s[38:39]
	v_cndmask_b32_e64 v128, v128, v124, s[38:39]
	v_pk_fma_f32 v[124:125], v[122:123], s[6:7], v[138:139] op_sel_hi:[1,0,0]
	v_pk_mul_f32 v[186:187], v[186:187], s[62:63] op_sel_hi:[1,0]
	v_pk_fma_f32 v[124:125], v[122:123], v[124:125], s[26:27] op_sel_hi:[1,1,0]
	v_exp_f32_e32 v186, v186
	v_exp_f32_e32 v187, v187
	v_pk_fma_f32 v[124:125], v[122:123], v[124:125], s[30:31] op_sel_hi:[1,1,0]
	v_pk_fma_f32 v[124:125], v[122:123], v[124:125], s[40:41] op_sel_hi:[1,1,0]
	v_lshl_add_u64 v[162:163], v[162:163], 1, v[158:159]
	v_pk_mul_f32 v[122:123], v[122:123], v[124:125]
	v_pk_mul_f32 v[124:125], v[184:185], v[184:185]
	v_pk_mul_f32 v[122:123], v[186:187], v[122:123]
	v_pk_mul_f32 v[124:125], v[124:125], s[62:63] op_sel_hi:[1,0]
	v_max_f32_e32 v186, 0, v126
	v_max_f32_e32 v187, 0, v127
	v_fma_f32 v122, -|v126|, v122, v186
	v_fma_f32 v123, -|v127|, v123, v187
	v_fma_f32 v126, |v184|, s2, 1.0
	v_fma_f32 v127, |v185|, s2, 1.0
	v_rcp_f32_e32 v126, v126
	v_rcp_f32_e32 v127, v127
	v_exp_f32_e32 v124, v124
	v_exp_f32_e32 v125, v125
	v_pk_fma_f32 v[186:187], v[126:127], s[6:7], v[138:139] op_sel_hi:[1,0,0]
	s_nop 0
	v_pk_fma_f32 v[186:187], v[126:127], v[186:187], s[26:27] op_sel_hi:[1,1,0]
	s_nop 0
	v_pk_fma_f32 v[186:187], v[126:127], v[186:187], s[30:31] op_sel_hi:[1,1,0]
	s_nop 0
	v_pk_fma_f32 v[186:187], v[126:127], v[186:187], s[40:41] op_sel_hi:[1,1,0]
	s_nop 0
	v_pk_mul_f32 v[126:127], v[126:127], v[186:187]
	v_pk_mul_f32 v[186:187], v[166:167], v[166:167]
	v_pk_mul_f32 v[124:125], v[124:125], v[126:127]
	v_pk_mul_f32 v[186:187], v[186:187], s[62:63] op_sel_hi:[1,0]
	v_max_f32_e32 v126, 0, v184
	v_max_f32_e32 v127, 0, v185
	v_fma_f32 v124, -|v184|, v124, v126
	v_fma_f32 v125, -|v185|, v125, v127
	v_exp_f32_e32 v186, v186
	v_exp_f32_e32 v187, v187
	v_fma_f32 v126, |v166|, s2, 1.0
	v_fma_f32 v127, |v167|, s2, 1.0
	v_rcp_f32_e32 v126, v126
	v_rcp_f32_e32 v127, v127
	s_nop 0
	v_pk_fma_f32 v[184:185], v[126:127], s[6:7], v[138:139] op_sel_hi:[1,0,0]
	s_nop 0
	v_pk_fma_f32 v[184:185], v[126:127], v[184:185], s[26:27] op_sel_hi:[1,1,0]
	s_nop 0
	v_pk_fma_f32 v[184:185], v[126:127], v[184:185], s[30:31] op_sel_hi:[1,1,0]
	s_nop 0
	v_pk_fma_f32 v[184:185], v[126:127], v[184:185], s[40:41] op_sel_hi:[1,1,0]
	s_nop 0
	v_pk_mul_f32 v[126:127], v[126:127], v[184:185]
	v_pk_mul_f32 v[184:185], v[128:129], v[128:129]
	v_pk_mul_f32 v[126:127], v[186:187], v[126:127]
	v_pk_mul_f32 v[184:185], v[184:185], s[62:63] op_sel_hi:[1,0]
	v_max_f32_e32 v186, 0, v166
	v_max_f32_e32 v187, 0, v167
	v_fma_f32 v126, -|v166|, v126, v186
	v_fma_f32 v127, -|v167|, v127, v187
	v_fma_f32 v166, |v128|, s2, 1.0
	v_fma_f32 v167, |v129|, s2, 1.0
	v_rcp_f32_e32 v166, v166
	v_rcp_f32_e32 v167, v167
	v_exp_f32_e32 v184, v184
	v_exp_f32_e32 v185, v185
	v_pk_fma_f32 v[186:187], v[166:167], s[6:7], v[138:139] op_sel_hi:[1,0,0]
	s_nop 0
	v_pk_fma_f32 v[186:187], v[166:167], v[186:187], s[26:27] op_sel_hi:[1,1,0]
	s_nop 0
	v_pk_fma_f32 v[186:187], v[166:167], v[186:187], s[30:31] op_sel_hi:[1,1,0]
	s_nop 0
	v_pk_fma_f32 v[186:187], v[166:167], v[186:187], s[40:41] op_sel_hi:[1,1,0]
	s_nop 0
	v_pk_mul_f32 v[166:167], v[166:167], v[186:187]
	v_cvt_pk_bf16_f32 v186, v126, v127
	v_pk_mul_f32 v[166:167], v[184:185], v[166:167]
	s_nop 0
	v_max_f32_e32 v184, 0, v128
	v_max_f32_e32 v185, 0, v129
	v_fma_f32 v166, -|v128|, v166, v184
	v_fma_f32 v167, -|v129|, v167, v185
	s_nop 0
	v_mov_b32_e32 v128, v166
	v_cvt_pk_bf16_f32 v184, v122, v123
	s_nop 0
	v_mov_b32_e32 v129, v167
	v_pk_fma_f32 v[166:167], v[118:119], v[38:39], v[164:165] op_sel_hi:[1,1,0]
	v_pk_fma_f32 v[118:119], v[118:119], v[164:165], v[38:39] op_sel_hi:[1,0,1]
	v_cvt_pk_bf16_f32 v185, v124, v125
	v_cndmask_b32_e64 v118, v166, v118, s[38:39]
	v_cndmask_b32_e64 v119, v167, v119, s[38:39]
	v_pk_fma_f32 v[166:167], v[114:115], v[46:47], v[164:165] op_sel_hi:[1,1,0]
	v_pk_fma_f32 v[114:115], v[114:115], v[164:165], v[46:47] op_sel_hi:[1,0,1]
	v_cvt_pk_bf16_f32 v187, v128, v129
	v_cndmask_b32_e64 v166, v166, v114, s[38:39]
	v_cndmask_b32_e64 v167, v167, v115, s[38:39]
	v_fma_f32 v114, |v118|, s2, 1.0
	v_fma_f32 v115, |v119|, s2, 1.0
	global_store_dwordx4 v[162:163], v[184:187], off
	v_rcp_f32_e32 v114, v114
	v_rcp_f32_e32 v115, v115
	v_pk_fma_f32 v[184:185], v[120:121], v[40:41], v[164:165] op_sel_hi:[1,1,0]
	v_pk_fma_f32 v[120:121], v[120:121], v[164:165], v[40:41] op_sel_hi:[1,0,1]
	v_pk_mul_f32 v[186:187], v[118:119], v[118:119]
	v_cndmask_b32_e64 v185, v185, v121, s[38:39]
	v_cndmask_b32_e64 v184, v184, v120, s[38:39]
	v_pk_fma_f32 v[120:121], v[116:117], v[48:49], v[164:165] op_sel_hi:[1,1,0]
	v_pk_fma_f32 v[116:117], v[116:117], v[164:165], v[48:49] op_sel_hi:[1,0,1]
	v_pk_mul_f32 v[186:187], v[186:187], s[62:63] op_sel_hi:[1,0]
	v_cndmask_b32_e64 v121, v121, v117, s[38:39]
	v_cndmask_b32_e64 v120, v120, v116, s[38:39]
	v_pk_fma_f32 v[116:117], v[114:115], s[6:7], v[138:139] op_sel_hi:[1,0,0]
	v_exp_f32_e32 v186, v186
	v_pk_fma_f32 v[116:117], v[114:115], v[116:117], s[26:27] op_sel_hi:[1,1,0]
	v_exp_f32_e32 v187, v187
	v_pk_fma_f32 v[116:117], v[114:115], v[116:117], s[30:31] op_sel_hi:[1,1,0]
	v_pk_fma_f32 v[116:117], v[114:115], v[116:117], s[40:41] op_sel_hi:[1,1,0]
	s_nop 0
	v_pk_mul_f32 v[114:115], v[114:115], v[116:117]
	v_pk_mul_f32 v[116:117], v[184:185], v[184:185]
	v_pk_mul_f32 v[114:115], v[186:187], v[114:115]
	v_pk_mul_f32 v[116:117], v[116:117], s[62:63] op_sel_hi:[1,0]
	v_max_f32_e32 v186, 0, v118
	v_max_f32_e32 v187, 0, v119
	v_fma_f32 v114, -|v118|, v114, v186
	v_fma_f32 v115, -|v119|, v115, v187
	v_fma_f32 v118, |v184|, s2, 1.0
	v_fma_f32 v119, |v185|, s2, 1.0
	v_rcp_f32_e32 v118, v118
	v_rcp_f32_e32 v119, v119
	v_exp_f32_e32 v116, v116
	v_exp_f32_e32 v117, v117
	v_pk_fma_f32 v[186:187], v[118:119], s[6:7], v[138:139] op_sel_hi:[1,0,0]
	s_nop 0
	v_pk_fma_f32 v[186:187], v[118:119], v[186:187], s[26:27] op_sel_hi:[1,1,0]
	s_nop 0
	v_pk_fma_f32 v[186:187], v[118:119], v[186:187], s[30:31] op_sel_hi:[1,1,0]
	s_nop 0
	v_pk_fma_f32 v[186:187], v[118:119], v[186:187], s[40:41] op_sel_hi:[1,1,0]
	s_nop 0
	v_pk_mul_f32 v[118:119], v[118:119], v[186:187]
	v_pk_mul_f32 v[186:187], v[166:167], v[166:167]
	v_pk_mul_f32 v[116:117], v[116:117], v[118:119]
	v_pk_mul_f32 v[186:187], v[186:187], s[62:63] op_sel_hi:[1,0]
	v_max_f32_e32 v118, 0, v184
	v_max_f32_e32 v119, 0, v185
	v_fma_f32 v116, -|v184|, v116, v118
	v_fma_f32 v117, -|v185|, v117, v119
	v_exp_f32_e32 v186, v186
	v_exp_f32_e32 v187, v187
	v_fma_f32 v118, |v166|, s2, 1.0
	v_fma_f32 v119, |v167|, s2, 1.0
	v_rcp_f32_e32 v118, v118
	v_rcp_f32_e32 v119, v119
	s_nop 0
	v_pk_fma_f32 v[184:185], v[118:119], s[6:7], v[138:139] op_sel_hi:[1,0,0]
	s_nop 0
	v_pk_fma_f32 v[184:185], v[118:119], v[184:185], s[26:27] op_sel_hi:[1,1,0]
	s_nop 0
	v_pk_fma_f32 v[184:185], v[118:119], v[184:185], s[30:31] op_sel_hi:[1,1,0]
	s_nop 0
	v_pk_fma_f32 v[184:185], v[118:119], v[184:185], s[40:41] op_sel_hi:[1,1,0]
	s_nop 0
	v_pk_mul_f32 v[118:119], v[118:119], v[184:185]
	v_pk_mul_f32 v[184:185], v[120:121], v[120:121]
	v_pk_mul_f32 v[118:119], v[186:187], v[118:119]
	v_pk_mul_f32 v[184:185], v[184:185], s[62:63] op_sel_hi:[1,0]
	v_max_f32_e32 v186, 0, v166
	v_max_f32_e32 v187, 0, v167
	v_fma_f32 v118, -|v166|, v118, v186
	v_fma_f32 v119, -|v167|, v119, v187
	v_fma_f32 v166, |v120|, s2, 1.0
	v_fma_f32 v167, |v121|, s2, 1.0
	v_rcp_f32_e32 v166, v166
	v_rcp_f32_e32 v167, v167
	v_exp_f32_e32 v184, v184
	v_exp_f32_e32 v185, v185
	v_pk_fma_f32 v[186:187], v[166:167], s[6:7], v[138:139] op_sel_hi:[1,0,0]
	s_nop 0
	v_pk_fma_f32 v[186:187], v[166:167], v[186:187], s[26:27] op_sel_hi:[1,1,0]
	s_nop 0
	v_pk_fma_f32 v[186:187], v[166:167], v[186:187], s[30:31] op_sel_hi:[1,1,0]
	s_nop 0
	v_pk_fma_f32 v[186:187], v[166:167], v[186:187], s[40:41] op_sel_hi:[1,1,0]
	s_nop 0
	v_pk_mul_f32 v[166:167], v[166:167], v[186:187]
	v_cvt_pk_bf16_f32 v186, v118, v119
	v_pk_mul_f32 v[166:167], v[184:185], v[166:167]
	s_nop 0
	v_max_f32_e32 v184, 0, v120
	v_max_f32_e32 v185, 0, v121
	v_fma_f32 v166, -|v120|, v166, v184
	v_fma_f32 v167, -|v121|, v167, v185
	s_nop 0
	v_mov_b32_e32 v120, v166
	v_cvt_pk_bf16_f32 v184, v114, v115
	s_nop 0
	v_mov_b32_e32 v121, v167
	v_cvt_pk_bf16_f32 v185, v116, v117
	v_cvt_pk_bf16_f32 v187, v120, v121
	global_store_dwordx4 v[162:163], v[184:187], off offset:256
	v_fmamk_f32 v162, v183, 0x3a800000, v202
	v_cmp_gt_f32_e32 vcc, s68, v162
	v_mul_f32_e32 v163, 0x4b800000, v162
	s_nop 0
	v_cndmask_b32_e32 v162, v162, v163, vcc
	v_rsq_f32_e32 v162, v162
	s_nop 0
	v_mul_f32_e32 v163, 0x45800000, v162
	v_cndmask_b32_e32 v162, v162, v163, vcc
	v_cndmask_b32_e64 v164, v183, v162, s[38:39]
	v_pk_fma_f32 v[166:167], v[110:111], v[34:35], v[164:165] op_sel_hi:[1,1,0]
	v_pk_fma_f32 v[110:111], v[110:111], v[164:165], v[34:35] op_sel_hi:[1,0,1]
	v_mad_i64_i32 v[162:163], s[0:1], s4, v182, 0
	v_cndmask_b32_e64 v110, v166, v110, s[38:39]
	v_cndmask_b32_e64 v111, v167, v111, s[38:39]
	v_pk_fma_f32 v[166:167], v[106:107], v[42:43], v[164:165] op_sel_hi:[1,1,0]
	v_pk_fma_f32 v[106:107], v[106:107], v[164:165], v[42:43] op_sel_hi:[1,0,1]
	v_pk_fma_f32 v[182:183], v[112:113], v[36:37], v[164:165] op_sel_hi:[1,1,0]
	v_cndmask_b32_e64 v166, v166, v106, s[38:39]
	v_cndmask_b32_e64 v167, v167, v107, s[38:39]
	v_fma_f32 v106, |v110|, s2, 1.0
	v_fma_f32 v107, |v111|, s2, 1.0
	v_pk_fma_f32 v[112:113], v[112:113], v[164:165], v[36:37] op_sel_hi:[1,0,1]
	v_rcp_f32_e32 v106, v106
	v_rcp_f32_e32 v107, v107
	v_cndmask_b32_e64 v183, v183, v113, s[38:39]
	v_cndmask_b32_e64 v182, v182, v112, s[38:39]
	v_pk_fma_f32 v[112:113], v[108:109], v[44:45], v[164:165] op_sel_hi:[1,1,0]
	v_pk_fma_f32 v[108:109], v[108:109], v[164:165], v[44:45] op_sel_hi:[1,0,1]
	v_pk_mul_f32 v[184:185], v[110:111], v[110:111]
	v_cndmask_b32_e64 v113, v113, v109, s[38:39]
	v_cndmask_b32_e64 v112, v112, v108, s[38:39]
	v_pk_fma_f32 v[108:109], v[106:107], s[6:7], v[138:139] op_sel_hi:[1,0,0]
	v_pk_mul_f32 v[184:185], v[184:185], s[62:63] op_sel_hi:[1,0]
	v_pk_fma_f32 v[108:109], v[106:107], v[108:109], s[26:27] op_sel_hi:[1,1,0]
	v_exp_f32_e32 v184, v184
	v_exp_f32_e32 v185, v185
	v_pk_fma_f32 v[108:109], v[106:107], v[108:109], s[30:31] op_sel_hi:[1,1,0]
	v_pk_fma_f32 v[108:109], v[106:107], v[108:109], s[40:41] op_sel_hi:[1,1,0]
	v_lshl_add_u64 v[162:163], v[162:163], 1, v[158:159]
	v_pk_mul_f32 v[106:107], v[106:107], v[108:109]
	v_pk_mul_f32 v[108:109], v[182:183], v[182:183]
	v_pk_mul_f32 v[106:107], v[184:185], v[106:107]
	v_pk_mul_f32 v[108:109], v[108:109], s[62:63] op_sel_hi:[1,0]
	v_max_f32_e32 v184, 0, v110
	v_max_f32_e32 v185, 0, v111
	v_fma_f32 v106, -|v110|, v106, v184
	v_fma_f32 v107, -|v111|, v107, v185
	v_fma_f32 v110, |v182|, s2, 1.0
	v_fma_f32 v111, |v183|, s2, 1.0
	v_rcp_f32_e32 v110, v110
	v_rcp_f32_e32 v111, v111
	v_exp_f32_e32 v108, v108
	v_exp_f32_e32 v109, v109
	v_pk_fma_f32 v[184:185], v[110:111], s[6:7], v[138:139] op_sel_hi:[1,0,0]
	s_nop 0
	v_pk_fma_f32 v[184:185], v[110:111], v[184:185], s[26:27] op_sel_hi:[1,1,0]
	s_nop 0
	v_pk_fma_f32 v[184:185], v[110:111], v[184:185], s[30:31] op_sel_hi:[1,1,0]
	s_nop 0
	v_pk_fma_f32 v[184:185], v[110:111], v[184:185], s[40:41] op_sel_hi:[1,1,0]
	s_nop 0
	v_pk_mul_f32 v[110:111], v[110:111], v[184:185]
	v_pk_mul_f32 v[184:185], v[166:167], v[166:167]
	v_pk_mul_f32 v[108:109], v[108:109], v[110:111]
	v_pk_mul_f32 v[184:185], v[184:185], s[62:63] op_sel_hi:[1,0]
	v_max_f32_e32 v110, 0, v182
	v_max_f32_e32 v111, 0, v183
	v_fma_f32 v108, -|v182|, v108, v110
	v_fma_f32 v109, -|v183|, v109, v111
	v_exp_f32_e32 v184, v184
	v_exp_f32_e32 v185, v185
	v_fma_f32 v110, |v166|, s2, 1.0
	v_fma_f32 v111, |v167|, s2, 1.0
	v_rcp_f32_e32 v110, v110
	v_rcp_f32_e32 v111, v111
	s_nop 0
	v_pk_fma_f32 v[182:183], v[110:111], s[6:7], v[138:139] op_sel_hi:[1,0,0]
	s_nop 0
	v_pk_fma_f32 v[182:183], v[110:111], v[182:183], s[26:27] op_sel_hi:[1,1,0]
	s_nop 0
	v_pk_fma_f32 v[182:183], v[110:111], v[182:183], s[30:31] op_sel_hi:[1,1,0]
	s_nop 0
	v_pk_fma_f32 v[182:183], v[110:111], v[182:183], s[40:41] op_sel_hi:[1,1,0]
	s_nop 0
	v_pk_mul_f32 v[110:111], v[110:111], v[182:183]
	v_pk_mul_f32 v[182:183], v[112:113], v[112:113]
	v_pk_mul_f32 v[110:111], v[184:185], v[110:111]
	v_pk_mul_f32 v[182:183], v[182:183], s[62:63] op_sel_hi:[1,0]
	v_max_f32_e32 v184, 0, v166
	v_max_f32_e32 v185, 0, v167
	v_fma_f32 v110, -|v166|, v110, v184
	v_fma_f32 v111, -|v167|, v111, v185
	v_fma_f32 v166, |v112|, s2, 1.0
	v_fma_f32 v167, |v113|, s2, 1.0
	v_rcp_f32_e32 v166, v166
	v_rcp_f32_e32 v167, v167
	v_exp_f32_e32 v182, v182
	v_exp_f32_e32 v183, v183
	v_pk_fma_f32 v[184:185], v[166:167], s[6:7], v[138:139] op_sel_hi:[1,0,0]
	s_nop 0
	v_pk_fma_f32 v[184:185], v[166:167], v[184:185], s[26:27] op_sel_hi:[1,1,0]
	s_nop 0
	v_pk_fma_f32 v[184:185], v[166:167], v[184:185], s[30:31] op_sel_hi:[1,1,0]
	s_nop 0
	v_pk_fma_f32 v[184:185], v[166:167], v[184:185], s[40:41] op_sel_hi:[1,1,0]
	s_nop 0
	v_pk_mul_f32 v[166:167], v[166:167], v[184:185]
	v_cvt_pk_bf16_f32 v184, v110, v111
	v_pk_mul_f32 v[166:167], v[182:183], v[166:167]
	s_nop 0
	v_max_f32_e32 v182, 0, v112
	v_max_f32_e32 v183, 0, v113
	v_fma_f32 v166, -|v112|, v166, v182
	v_fma_f32 v167, -|v113|, v167, v183
	s_nop 0
	v_mov_b32_e32 v112, v166
	v_cvt_pk_bf16_f32 v182, v106, v107
	s_nop 0
	v_mov_b32_e32 v113, v167
	v_pk_fma_f32 v[166:167], v[102:103], v[38:39], v[164:165] op_sel_hi:[1,1,0]
	v_pk_fma_f32 v[102:103], v[102:103], v[164:165], v[38:39] op_sel_hi:[1,0,1]
	v_cvt_pk_bf16_f32 v183, v108, v109
	v_cndmask_b32_e64 v102, v166, v102, s[38:39]
	v_cndmask_b32_e64 v103, v167, v103, s[38:39]
	v_pk_fma_f32 v[166:167], v[98:99], v[46:47], v[164:165] op_sel_hi:[1,1,0]
	v_pk_fma_f32 v[98:99], v[98:99], v[164:165], v[46:47] op_sel_hi:[1,0,1]
	v_cvt_pk_bf16_f32 v185, v112, v113
	v_cndmask_b32_e64 v166, v166, v98, s[38:39]
	v_cndmask_b32_e64 v167, v167, v99, s[38:39]
	v_fma_f32 v98, |v102|, s2, 1.0
	v_fma_f32 v99, |v103|, s2, 1.0
	global_store_dwordx4 v[162:163], v[182:185], off
	v_rcp_f32_e32 v98, v98
	v_rcp_f32_e32 v99, v99
	v_pk_fma_f32 v[182:183], v[104:105], v[40:41], v[164:165] op_sel_hi:[1,1,0]
	v_pk_fma_f32 v[104:105], v[104:105], v[164:165], v[40:41] op_sel_hi:[1,0,1]
	v_pk_mul_f32 v[184:185], v[102:103], v[102:103]
	v_cndmask_b32_e64 v183, v183, v105, s[38:39]
	v_cndmask_b32_e64 v182, v182, v104, s[38:39]
	v_pk_fma_f32 v[104:105], v[100:101], v[48:49], v[164:165] op_sel_hi:[1,1,0]
	v_pk_fma_f32 v[100:101], v[100:101], v[164:165], v[48:49] op_sel_hi:[1,0,1]
	v_pk_mul_f32 v[184:185], v[184:185], s[62:63] op_sel_hi:[1,0]
	v_cndmask_b32_e64 v105, v105, v101, s[38:39]
	v_cndmask_b32_e64 v104, v104, v100, s[38:39]
	v_pk_fma_f32 v[100:101], v[98:99], s[6:7], v[138:139] op_sel_hi:[1,0,0]
	v_exp_f32_e32 v184, v184
	v_pk_fma_f32 v[100:101], v[98:99], v[100:101], s[26:27] op_sel_hi:[1,1,0]
	v_exp_f32_e32 v185, v185
	v_pk_fma_f32 v[100:101], v[98:99], v[100:101], s[30:31] op_sel_hi:[1,1,0]
	v_pk_fma_f32 v[100:101], v[98:99], v[100:101], s[40:41] op_sel_hi:[1,1,0]
	s_nop 0
	v_pk_mul_f32 v[98:99], v[98:99], v[100:101]
	v_pk_mul_f32 v[100:101], v[182:183], v[182:183]
	v_pk_mul_f32 v[98:99], v[184:185], v[98:99]
	v_pk_mul_f32 v[100:101], v[100:101], s[62:63] op_sel_hi:[1,0]
	v_max_f32_e32 v184, 0, v102
	v_max_f32_e32 v185, 0, v103
	v_fma_f32 v98, -|v102|, v98, v184
	v_fma_f32 v99, -|v103|, v99, v185
	v_fma_f32 v102, |v182|, s2, 1.0
	v_fma_f32 v103, |v183|, s2, 1.0
	v_rcp_f32_e32 v102, v102
	v_rcp_f32_e32 v103, v103
	v_exp_f32_e32 v100, v100
	v_exp_f32_e32 v101, v101
	v_pk_fma_f32 v[184:185], v[102:103], s[6:7], v[138:139] op_sel_hi:[1,0,0]
	s_nop 0
	v_pk_fma_f32 v[184:185], v[102:103], v[184:185], s[26:27] op_sel_hi:[1,1,0]
	s_nop 0
	v_pk_fma_f32 v[184:185], v[102:103], v[184:185], s[30:31] op_sel_hi:[1,1,0]
	s_nop 0
	v_pk_fma_f32 v[184:185], v[102:103], v[184:185], s[40:41] op_sel_hi:[1,1,0]
	s_nop 0
	v_pk_mul_f32 v[102:103], v[102:103], v[184:185]
	v_pk_mul_f32 v[184:185], v[166:167], v[166:167]
	v_pk_mul_f32 v[100:101], v[100:101], v[102:103]
	v_pk_mul_f32 v[184:185], v[184:185], s[62:63] op_sel_hi:[1,0]
	v_max_f32_e32 v102, 0, v182
	v_max_f32_e32 v103, 0, v183
	v_fma_f32 v100, -|v182|, v100, v102
	v_fma_f32 v101, -|v183|, v101, v103
	v_exp_f32_e32 v184, v184
	v_exp_f32_e32 v185, v185
	v_fma_f32 v102, |v166|, s2, 1.0
	v_fma_f32 v103, |v167|, s2, 1.0
	v_rcp_f32_e32 v102, v102
	v_rcp_f32_e32 v103, v103
	s_nop 0
	v_pk_fma_f32 v[182:183], v[102:103], s[6:7], v[138:139] op_sel_hi:[1,0,0]
	s_nop 0
	v_pk_fma_f32 v[182:183], v[102:103], v[182:183], s[26:27] op_sel_hi:[1,1,0]
	s_nop 0
	v_pk_fma_f32 v[182:183], v[102:103], v[182:183], s[30:31] op_sel_hi:[1,1,0]
	s_nop 0
	v_pk_fma_f32 v[182:183], v[102:103], v[182:183], s[40:41] op_sel_hi:[1,1,0]
	s_nop 0
	v_pk_mul_f32 v[102:103], v[102:103], v[182:183]
	v_pk_mul_f32 v[182:183], v[104:105], v[104:105]
	v_pk_mul_f32 v[102:103], v[184:185], v[102:103]
	v_pk_mul_f32 v[182:183], v[182:183], s[62:63] op_sel_hi:[1,0]
	v_max_f32_e32 v184, 0, v166
	v_max_f32_e32 v185, 0, v167
	v_fma_f32 v102, -|v166|, v102, v184
	v_fma_f32 v103, -|v167|, v103, v185
	v_fma_f32 v166, |v104|, s2, 1.0
	v_fma_f32 v167, |v105|, s2, 1.0
	v_rcp_f32_e32 v166, v166
	v_rcp_f32_e32 v167, v167
	v_exp_f32_e32 v182, v182
	v_exp_f32_e32 v183, v183
	v_pk_fma_f32 v[184:185], v[166:167], s[6:7], v[138:139] op_sel_hi:[1,0,0]
	s_nop 0
	v_pk_fma_f32 v[184:185], v[166:167], v[184:185], s[26:27] op_sel_hi:[1,1,0]
	s_nop 0
	v_pk_fma_f32 v[184:185], v[166:167], v[184:185], s[30:31] op_sel_hi:[1,1,0]
	s_nop 0
	v_pk_fma_f32 v[184:185], v[166:167], v[184:185], s[40:41] op_sel_hi:[1,1,0]
	s_nop 0
	v_pk_mul_f32 v[166:167], v[166:167], v[184:185]
	v_cvt_pk_bf16_f32 v184, v102, v103
	v_pk_mul_f32 v[166:167], v[182:183], v[166:167]
	s_nop 0
	v_max_f32_e32 v182, 0, v104
	v_max_f32_e32 v183, 0, v105
	v_fma_f32 v166, -|v104|, v166, v182
	v_fma_f32 v167, -|v105|, v167, v183
	s_nop 0
	v_mov_b32_e32 v104, v166
	v_cvt_pk_bf16_f32 v182, v98, v99
	s_nop 0
	v_mov_b32_e32 v105, v167
	v_cvt_pk_bf16_f32 v183, v100, v101
	v_cvt_pk_bf16_f32 v185, v104, v105
	global_store_dwordx4 v[162:163], v[182:185], off offset:256
	v_fmamk_f32 v162, v181, 0x3a800000, v202
	v_cmp_gt_f32_e32 vcc, s68, v162
	v_mul_f32_e32 v163, 0x4b800000, v162
	s_nop 0
	v_cndmask_b32_e32 v162, v162, v163, vcc
	v_rsq_f32_e32 v162, v162
	s_nop 0
	v_mul_f32_e32 v163, 0x45800000, v162
	v_cndmask_b32_e32 v162, v162, v163, vcc
	v_cndmask_b32_e64 v164, v181, v162, s[38:39]
	v_pk_fma_f32 v[166:167], v[94:95], v[34:35], v[164:165] op_sel_hi:[1,1,0]
	v_pk_fma_f32 v[94:95], v[94:95], v[164:165], v[34:35] op_sel_hi:[1,0,1]
	v_mad_i64_i32 v[162:163], s[0:1], s4, v180, 0
	v_cndmask_b32_e64 v94, v166, v94, s[38:39]
	v_cndmask_b32_e64 v95, v167, v95, s[38:39]
	v_pk_fma_f32 v[166:167], v[90:91], v[42:43], v[164:165] op_sel_hi:[1,1,0]
	v_pk_fma_f32 v[90:91], v[90:91], v[164:165], v[42:43] op_sel_hi:[1,0,1]
	v_pk_fma_f32 v[180:181], v[96:97], v[36:37], v[164:165] op_sel_hi:[1,1,0]
	v_cndmask_b32_e64 v166, v166, v90, s[38:39]
	v_cndmask_b32_e64 v167, v167, v91, s[38:39]
	v_fma_f32 v90, |v94|, s2, 1.0
	v_fma_f32 v91, |v95|, s2, 1.0
	v_pk_fma_f32 v[96:97], v[96:97], v[164:165], v[36:37] op_sel_hi:[1,0,1]
	v_rcp_f32_e32 v90, v90
	v_rcp_f32_e32 v91, v91
	v_cndmask_b32_e64 v181, v181, v97, s[38:39]
	v_cndmask_b32_e64 v180, v180, v96, s[38:39]
	v_pk_fma_f32 v[96:97], v[92:93], v[44:45], v[164:165] op_sel_hi:[1,1,0]
	v_pk_fma_f32 v[92:93], v[92:93], v[164:165], v[44:45] op_sel_hi:[1,0,1]
	v_pk_mul_f32 v[182:183], v[94:95], v[94:95]
	v_cndmask_b32_e64 v97, v97, v93, s[38:39]
	v_cndmask_b32_e64 v96, v96, v92, s[38:39]
	v_pk_fma_f32 v[92:93], v[90:91], s[6:7], v[138:139] op_sel_hi:[1,0,0]
	v_pk_mul_f32 v[182:183], v[182:183], s[62:63] op_sel_hi:[1,0]
	v_pk_fma_f32 v[92:93], v[90:91], v[92:93], s[26:27] op_sel_hi:[1,1,0]
	v_exp_f32_e32 v182, v182
	v_exp_f32_e32 v183, v183
	v_pk_fma_f32 v[92:93], v[90:91], v[92:93], s[30:31] op_sel_hi:[1,1,0]
	v_pk_fma_f32 v[92:93], v[90:91], v[92:93], s[40:41] op_sel_hi:[1,1,0]
	v_lshl_add_u64 v[162:163], v[162:163], 1, v[158:159]
	v_pk_mul_f32 v[90:91], v[90:91], v[92:93]
	v_pk_mul_f32 v[92:93], v[180:181], v[180:181]
	v_pk_mul_f32 v[90:91], v[182:183], v[90:91]
	v_pk_mul_f32 v[92:93], v[92:93], s[62:63] op_sel_hi:[1,0]
	v_max_f32_e32 v182, 0, v94
	v_max_f32_e32 v183, 0, v95
	v_fma_f32 v90, -|v94|, v90, v182
	v_fma_f32 v91, -|v95|, v91, v183
	v_fma_f32 v94, |v180|, s2, 1.0
	v_fma_f32 v95, |v181|, s2, 1.0
	v_rcp_f32_e32 v94, v94
	v_rcp_f32_e32 v95, v95
	v_exp_f32_e32 v92, v92
	v_exp_f32_e32 v93, v93
	v_pk_fma_f32 v[182:183], v[94:95], s[6:7], v[138:139] op_sel_hi:[1,0,0]
	s_nop 0
	v_pk_fma_f32 v[182:183], v[94:95], v[182:183], s[26:27] op_sel_hi:[1,1,0]
	s_nop 0
	v_pk_fma_f32 v[182:183], v[94:95], v[182:183], s[30:31] op_sel_hi:[1,1,0]
	s_nop 0
	v_pk_fma_f32 v[182:183], v[94:95], v[182:183], s[40:41] op_sel_hi:[1,1,0]
	s_nop 0
	v_pk_mul_f32 v[94:95], v[94:95], v[182:183]
	v_pk_mul_f32 v[182:183], v[166:167], v[166:167]
	v_pk_mul_f32 v[92:93], v[92:93], v[94:95]
	v_pk_mul_f32 v[182:183], v[182:183], s[62:63] op_sel_hi:[1,0]
	v_max_f32_e32 v94, 0, v180
	v_max_f32_e32 v95, 0, v181
	v_fma_f32 v92, -|v180|, v92, v94
	v_fma_f32 v93, -|v181|, v93, v95
	v_exp_f32_e32 v182, v182
	v_exp_f32_e32 v183, v183
	v_fma_f32 v94, |v166|, s2, 1.0
	v_fma_f32 v95, |v167|, s2, 1.0
	v_rcp_f32_e32 v94, v94
	v_rcp_f32_e32 v95, v95
	s_nop 0
	v_pk_fma_f32 v[180:181], v[94:95], s[6:7], v[138:139] op_sel_hi:[1,0,0]
	s_nop 0
	v_pk_fma_f32 v[180:181], v[94:95], v[180:181], s[26:27] op_sel_hi:[1,1,0]
	s_nop 0
	v_pk_fma_f32 v[180:181], v[94:95], v[180:181], s[30:31] op_sel_hi:[1,1,0]
	s_nop 0
	v_pk_fma_f32 v[180:181], v[94:95], v[180:181], s[40:41] op_sel_hi:[1,1,0]
	s_nop 0
	v_pk_mul_f32 v[94:95], v[94:95], v[180:181]
	v_pk_mul_f32 v[180:181], v[96:97], v[96:97]
	v_pk_mul_f32 v[94:95], v[182:183], v[94:95]
	v_pk_mul_f32 v[180:181], v[180:181], s[62:63] op_sel_hi:[1,0]
	v_max_f32_e32 v182, 0, v166
	v_max_f32_e32 v183, 0, v167
	v_fma_f32 v94, -|v166|, v94, v182
	v_fma_f32 v95, -|v167|, v95, v183
	v_fma_f32 v166, |v96|, s2, 1.0
	v_fma_f32 v167, |v97|, s2, 1.0
	v_rcp_f32_e32 v166, v166
	v_rcp_f32_e32 v167, v167
	v_exp_f32_e32 v180, v180
	v_exp_f32_e32 v181, v181
	v_pk_fma_f32 v[182:183], v[166:167], s[6:7], v[138:139] op_sel_hi:[1,0,0]
	s_nop 0
	v_pk_fma_f32 v[182:183], v[166:167], v[182:183], s[26:27] op_sel_hi:[1,1,0]
	s_nop 0
	v_pk_fma_f32 v[182:183], v[166:167], v[182:183], s[30:31] op_sel_hi:[1,1,0]
	s_nop 0
	v_pk_fma_f32 v[182:183], v[166:167], v[182:183], s[40:41] op_sel_hi:[1,1,0]
	s_nop 0
	v_pk_mul_f32 v[166:167], v[166:167], v[182:183]
	v_cvt_pk_bf16_f32 v182, v94, v95
	v_pk_mul_f32 v[166:167], v[180:181], v[166:167]
	s_nop 0
	v_max_f32_e32 v180, 0, v96
	v_max_f32_e32 v181, 0, v97
	v_fma_f32 v166, -|v96|, v166, v180
	v_fma_f32 v167, -|v97|, v167, v181
	s_nop 0
	v_mov_b32_e32 v96, v166
	v_cvt_pk_bf16_f32 v180, v90, v91
	s_nop 0
	v_mov_b32_e32 v97, v167
	v_pk_fma_f32 v[166:167], v[86:87], v[38:39], v[164:165] op_sel_hi:[1,1,0]
	v_pk_fma_f32 v[86:87], v[86:87], v[164:165], v[38:39] op_sel_hi:[1,0,1]
	v_cvt_pk_bf16_f32 v181, v92, v93
	v_cndmask_b32_e64 v86, v166, v86, s[38:39]
	v_cndmask_b32_e64 v87, v167, v87, s[38:39]
	v_pk_fma_f32 v[166:167], v[82:83], v[46:47], v[164:165] op_sel_hi:[1,1,0]
	v_pk_fma_f32 v[82:83], v[82:83], v[164:165], v[46:47] op_sel_hi:[1,0,1]
	v_cvt_pk_bf16_f32 v183, v96, v97
	v_cndmask_b32_e64 v166, v166, v82, s[38:39]
	v_cndmask_b32_e64 v167, v167, v83, s[38:39]
	v_fma_f32 v82, |v86|, s2, 1.0
	v_fma_f32 v83, |v87|, s2, 1.0
	global_store_dwordx4 v[162:163], v[180:183], off
	v_rcp_f32_e32 v82, v82
	v_rcp_f32_e32 v83, v83
	v_pk_fma_f32 v[180:181], v[88:89], v[40:41], v[164:165] op_sel_hi:[1,1,0]
	v_pk_fma_f32 v[88:89], v[88:89], v[164:165], v[40:41] op_sel_hi:[1,0,1]
	v_pk_mul_f32 v[182:183], v[86:87], v[86:87]
	v_cndmask_b32_e64 v181, v181, v89, s[38:39]
	v_cndmask_b32_e64 v180, v180, v88, s[38:39]
	v_pk_fma_f32 v[88:89], v[84:85], v[48:49], v[164:165] op_sel_hi:[1,1,0]
	v_pk_fma_f32 v[84:85], v[84:85], v[164:165], v[48:49] op_sel_hi:[1,0,1]
	v_pk_mul_f32 v[182:183], v[182:183], s[62:63] op_sel_hi:[1,0]
	v_cndmask_b32_e64 v89, v89, v85, s[38:39]
	v_cndmask_b32_e64 v88, v88, v84, s[38:39]
	v_pk_fma_f32 v[84:85], v[82:83], s[6:7], v[138:139] op_sel_hi:[1,0,0]
	v_exp_f32_e32 v182, v182
	v_pk_fma_f32 v[84:85], v[82:83], v[84:85], s[26:27] op_sel_hi:[1,1,0]
	v_exp_f32_e32 v183, v183
	v_pk_fma_f32 v[84:85], v[82:83], v[84:85], s[30:31] op_sel_hi:[1,1,0]
	v_pk_fma_f32 v[84:85], v[82:83], v[84:85], s[40:41] op_sel_hi:[1,1,0]
	s_nop 0
	v_pk_mul_f32 v[82:83], v[82:83], v[84:85]
	v_pk_mul_f32 v[84:85], v[180:181], v[180:181]
	v_pk_mul_f32 v[82:83], v[182:183], v[82:83]
	v_pk_mul_f32 v[84:85], v[84:85], s[62:63] op_sel_hi:[1,0]
	v_max_f32_e32 v182, 0, v86
	v_max_f32_e32 v183, 0, v87
	v_fma_f32 v82, -|v86|, v82, v182
	v_fma_f32 v83, -|v87|, v83, v183
	v_fma_f32 v86, |v180|, s2, 1.0
	v_fma_f32 v87, |v181|, s2, 1.0
	v_rcp_f32_e32 v86, v86
	v_rcp_f32_e32 v87, v87
	v_exp_f32_e32 v84, v84
	v_exp_f32_e32 v85, v85
	v_pk_fma_f32 v[182:183], v[86:87], s[6:7], v[138:139] op_sel_hi:[1,0,0]
	s_nop 0
	v_pk_fma_f32 v[182:183], v[86:87], v[182:183], s[26:27] op_sel_hi:[1,1,0]
	s_nop 0
	v_pk_fma_f32 v[182:183], v[86:87], v[182:183], s[30:31] op_sel_hi:[1,1,0]
	s_nop 0
	v_pk_fma_f32 v[182:183], v[86:87], v[182:183], s[40:41] op_sel_hi:[1,1,0]
	s_nop 0
	v_pk_mul_f32 v[86:87], v[86:87], v[182:183]
	v_pk_mul_f32 v[182:183], v[166:167], v[166:167]
	v_pk_mul_f32 v[84:85], v[84:85], v[86:87]
	v_pk_mul_f32 v[182:183], v[182:183], s[62:63] op_sel_hi:[1,0]
	v_max_f32_e32 v86, 0, v180
	v_max_f32_e32 v87, 0, v181
	v_fma_f32 v84, -|v180|, v84, v86
	v_fma_f32 v85, -|v181|, v85, v87
	v_exp_f32_e32 v182, v182
	v_exp_f32_e32 v183, v183
	v_fma_f32 v86, |v166|, s2, 1.0
	v_fma_f32 v87, |v167|, s2, 1.0
	v_rcp_f32_e32 v86, v86
	v_rcp_f32_e32 v87, v87
	s_nop 0
	v_pk_fma_f32 v[180:181], v[86:87], s[6:7], v[138:139] op_sel_hi:[1,0,0]
	s_nop 0
	v_pk_fma_f32 v[180:181], v[86:87], v[180:181], s[26:27] op_sel_hi:[1,1,0]
	s_nop 0
	v_pk_fma_f32 v[180:181], v[86:87], v[180:181], s[30:31] op_sel_hi:[1,1,0]
	s_nop 0
	v_pk_fma_f32 v[180:181], v[86:87], v[180:181], s[40:41] op_sel_hi:[1,1,0]
	s_nop 0
	v_pk_mul_f32 v[86:87], v[86:87], v[180:181]
	v_pk_mul_f32 v[180:181], v[88:89], v[88:89]
	v_pk_mul_f32 v[86:87], v[182:183], v[86:87]
	v_pk_mul_f32 v[180:181], v[180:181], s[62:63] op_sel_hi:[1,0]
	v_max_f32_e32 v182, 0, v166
	v_max_f32_e32 v183, 0, v167
	v_fma_f32 v86, -|v166|, v86, v182
	v_fma_f32 v87, -|v167|, v87, v183
	v_fma_f32 v166, |v88|, s2, 1.0
	v_fma_f32 v167, |v89|, s2, 1.0
	v_rcp_f32_e32 v166, v166
	v_rcp_f32_e32 v167, v167
	v_exp_f32_e32 v180, v180
	v_exp_f32_e32 v181, v181
	v_pk_fma_f32 v[182:183], v[166:167], s[6:7], v[138:139] op_sel_hi:[1,0,0]
	s_nop 0
	v_pk_fma_f32 v[182:183], v[166:167], v[182:183], s[26:27] op_sel_hi:[1,1,0]
	s_nop 0
	v_pk_fma_f32 v[182:183], v[166:167], v[182:183], s[30:31] op_sel_hi:[1,1,0]
	s_nop 0
	v_pk_fma_f32 v[182:183], v[166:167], v[182:183], s[40:41] op_sel_hi:[1,1,0]
	s_nop 0
	v_pk_mul_f32 v[166:167], v[166:167], v[182:183]
	v_cvt_pk_bf16_f32 v182, v86, v87
	v_pk_mul_f32 v[166:167], v[180:181], v[166:167]
	s_nop 0
	v_max_f32_e32 v180, 0, v88
	v_max_f32_e32 v181, 0, v89
	v_fma_f32 v166, -|v88|, v166, v180
	v_fma_f32 v167, -|v89|, v167, v181
	s_nop 0
	v_mov_b32_e32 v88, v166
	v_cvt_pk_bf16_f32 v180, v82, v83
	s_nop 0
	v_mov_b32_e32 v89, v167
	v_cvt_pk_bf16_f32 v181, v84, v85
	v_cvt_pk_bf16_f32 v183, v88, v89
	global_store_dwordx4 v[162:163], v[180:183], off offset:256
	v_fmamk_f32 v162, v179, 0x3a800000, v202
	v_cmp_gt_f32_e32 vcc, s68, v162
	v_mul_f32_e32 v163, 0x4b800000, v162
	s_nop 0
	v_cndmask_b32_e32 v162, v162, v163, vcc
	v_rsq_f32_e32 v162, v162
	s_nop 0
	v_mul_f32_e32 v163, 0x45800000, v162
	v_cndmask_b32_e32 v162, v162, v163, vcc
	v_cndmask_b32_e64 v164, v179, v162, s[38:39]
	v_pk_fma_f32 v[166:167], v[78:79], v[34:35], v[164:165] op_sel_hi:[1,1,0]
	v_pk_fma_f32 v[78:79], v[78:79], v[164:165], v[34:35] op_sel_hi:[1,0,1]
	v_mad_i64_i32 v[162:163], s[0:1], s4, v178, 0
	v_cndmask_b32_e64 v78, v166, v78, s[38:39]
	v_cndmask_b32_e64 v79, v167, v79, s[38:39]
	v_pk_fma_f32 v[166:167], v[74:75], v[42:43], v[164:165] op_sel_hi:[1,1,0]
	v_pk_fma_f32 v[74:75], v[74:75], v[164:165], v[42:43] op_sel_hi:[1,0,1]
	v_pk_fma_f32 v[178:179], v[80:81], v[36:37], v[164:165] op_sel_hi:[1,1,0]
	v_cndmask_b32_e64 v166, v166, v74, s[38:39]
	v_cndmask_b32_e64 v167, v167, v75, s[38:39]
	v_fma_f32 v74, |v78|, s2, 1.0
	v_fma_f32 v75, |v79|, s2, 1.0
	v_pk_fma_f32 v[80:81], v[80:81], v[164:165], v[36:37] op_sel_hi:[1,0,1]
	v_rcp_f32_e32 v74, v74
	v_rcp_f32_e32 v75, v75
	v_cndmask_b32_e64 v179, v179, v81, s[38:39]
	v_cndmask_b32_e64 v178, v178, v80, s[38:39]
	v_pk_fma_f32 v[80:81], v[76:77], v[44:45], v[164:165] op_sel_hi:[1,1,0]
	v_pk_fma_f32 v[76:77], v[76:77], v[164:165], v[44:45] op_sel_hi:[1,0,1]
	v_pk_mul_f32 v[180:181], v[78:79], v[78:79]
	v_cndmask_b32_e64 v81, v81, v77, s[38:39]
	v_cndmask_b32_e64 v80, v80, v76, s[38:39]
	v_pk_fma_f32 v[76:77], v[74:75], s[6:7], v[138:139] op_sel_hi:[1,0,0]
	v_pk_mul_f32 v[180:181], v[180:181], s[62:63] op_sel_hi:[1,0]
	v_pk_fma_f32 v[76:77], v[74:75], v[76:77], s[26:27] op_sel_hi:[1,1,0]
	v_exp_f32_e32 v180, v180
	v_exp_f32_e32 v181, v181
	v_pk_fma_f32 v[76:77], v[74:75], v[76:77], s[30:31] op_sel_hi:[1,1,0]
	v_pk_fma_f32 v[76:77], v[74:75], v[76:77], s[40:41] op_sel_hi:[1,1,0]
	v_lshl_add_u64 v[162:163], v[162:163], 1, v[158:159]
	v_pk_mul_f32 v[74:75], v[74:75], v[76:77]
	v_pk_mul_f32 v[76:77], v[178:179], v[178:179]
	v_pk_mul_f32 v[74:75], v[180:181], v[74:75]
	v_pk_mul_f32 v[76:77], v[76:77], s[62:63] op_sel_hi:[1,0]
	v_max_f32_e32 v180, 0, v78
	v_max_f32_e32 v181, 0, v79
	v_fma_f32 v74, -|v78|, v74, v180
	v_fma_f32 v75, -|v79|, v75, v181
	v_fma_f32 v78, |v178|, s2, 1.0
	v_fma_f32 v79, |v179|, s2, 1.0
	v_rcp_f32_e32 v78, v78
	v_rcp_f32_e32 v79, v79
	v_exp_f32_e32 v76, v76
	v_exp_f32_e32 v77, v77
	v_pk_fma_f32 v[180:181], v[78:79], s[6:7], v[138:139] op_sel_hi:[1,0,0]
	s_nop 0
	v_pk_fma_f32 v[180:181], v[78:79], v[180:181], s[26:27] op_sel_hi:[1,1,0]
	s_nop 0
	v_pk_fma_f32 v[180:181], v[78:79], v[180:181], s[30:31] op_sel_hi:[1,1,0]
	s_nop 0
	v_pk_fma_f32 v[180:181], v[78:79], v[180:181], s[40:41] op_sel_hi:[1,1,0]
	s_nop 0
	v_pk_mul_f32 v[78:79], v[78:79], v[180:181]
	v_pk_mul_f32 v[180:181], v[166:167], v[166:167]
	v_pk_mul_f32 v[76:77], v[76:77], v[78:79]
	v_pk_mul_f32 v[180:181], v[180:181], s[62:63] op_sel_hi:[1,0]
	v_max_f32_e32 v78, 0, v178
	v_max_f32_e32 v79, 0, v179
	v_fma_f32 v76, -|v178|, v76, v78
	v_fma_f32 v77, -|v179|, v77, v79
	v_exp_f32_e32 v180, v180
	v_exp_f32_e32 v181, v181
	v_fma_f32 v78, |v166|, s2, 1.0
	v_fma_f32 v79, |v167|, s2, 1.0
	v_rcp_f32_e32 v78, v78
	v_rcp_f32_e32 v79, v79
	s_nop 0
	v_pk_fma_f32 v[178:179], v[78:79], s[6:7], v[138:139] op_sel_hi:[1,0,0]
	s_nop 0
	v_pk_fma_f32 v[178:179], v[78:79], v[178:179], s[26:27] op_sel_hi:[1,1,0]
	s_nop 0
	v_pk_fma_f32 v[178:179], v[78:79], v[178:179], s[30:31] op_sel_hi:[1,1,0]
	s_nop 0
	v_pk_fma_f32 v[178:179], v[78:79], v[178:179], s[40:41] op_sel_hi:[1,1,0]
	s_nop 0
	v_pk_mul_f32 v[78:79], v[78:79], v[178:179]
	v_pk_mul_f32 v[178:179], v[80:81], v[80:81]
	v_pk_mul_f32 v[78:79], v[180:181], v[78:79]
	v_pk_mul_f32 v[178:179], v[178:179], s[62:63] op_sel_hi:[1,0]
	v_max_f32_e32 v180, 0, v166
	v_max_f32_e32 v181, 0, v167
	v_fma_f32 v78, -|v166|, v78, v180
	v_fma_f32 v79, -|v167|, v79, v181
	v_fma_f32 v166, |v80|, s2, 1.0
	v_fma_f32 v167, |v81|, s2, 1.0
	v_rcp_f32_e32 v166, v166
	v_rcp_f32_e32 v167, v167
	v_exp_f32_e32 v178, v178
	v_exp_f32_e32 v179, v179
	v_pk_fma_f32 v[180:181], v[166:167], s[6:7], v[138:139] op_sel_hi:[1,0,0]
	s_nop 0
	v_pk_fma_f32 v[180:181], v[166:167], v[180:181], s[26:27] op_sel_hi:[1,1,0]
	s_nop 0
	v_pk_fma_f32 v[180:181], v[166:167], v[180:181], s[30:31] op_sel_hi:[1,1,0]
	s_nop 0
	v_pk_fma_f32 v[180:181], v[166:167], v[180:181], s[40:41] op_sel_hi:[1,1,0]
	s_nop 0
	v_pk_mul_f32 v[166:167], v[166:167], v[180:181]
	v_cvt_pk_bf16_f32 v180, v78, v79
	v_pk_mul_f32 v[166:167], v[178:179], v[166:167]
	s_nop 0
	v_max_f32_e32 v178, 0, v80
	v_max_f32_e32 v179, 0, v81
	v_fma_f32 v166, -|v80|, v166, v178
	v_fma_f32 v167, -|v81|, v167, v179
	s_nop 0
	v_mov_b32_e32 v80, v166
	v_cvt_pk_bf16_f32 v178, v74, v75
	s_nop 0
	v_mov_b32_e32 v81, v167
	v_pk_fma_f32 v[166:167], v[70:71], v[38:39], v[164:165] op_sel_hi:[1,1,0]
	v_pk_fma_f32 v[70:71], v[70:71], v[164:165], v[38:39] op_sel_hi:[1,0,1]
	v_cvt_pk_bf16_f32 v179, v76, v77
	v_cndmask_b32_e64 v70, v166, v70, s[38:39]
	v_cndmask_b32_e64 v71, v167, v71, s[38:39]
	v_pk_fma_f32 v[166:167], v[66:67], v[46:47], v[164:165] op_sel_hi:[1,1,0]
	v_pk_fma_f32 v[66:67], v[66:67], v[164:165], v[46:47] op_sel_hi:[1,0,1]
	v_cvt_pk_bf16_f32 v181, v80, v81
	v_cndmask_b32_e64 v166, v166, v66, s[38:39]
	v_cndmask_b32_e64 v167, v167, v67, s[38:39]
	v_fma_f32 v66, |v70|, s2, 1.0
	v_fma_f32 v67, |v71|, s2, 1.0
	global_store_dwordx4 v[162:163], v[178:181], off
	v_rcp_f32_e32 v66, v66
	v_rcp_f32_e32 v67, v67
	v_pk_fma_f32 v[178:179], v[72:73], v[40:41], v[164:165] op_sel_hi:[1,1,0]
	v_pk_fma_f32 v[72:73], v[72:73], v[164:165], v[40:41] op_sel_hi:[1,0,1]
	v_pk_mul_f32 v[180:181], v[70:71], v[70:71]
	v_cndmask_b32_e64 v179, v179, v73, s[38:39]
	v_cndmask_b32_e64 v178, v178, v72, s[38:39]
	v_pk_fma_f32 v[72:73], v[68:69], v[48:49], v[164:165] op_sel_hi:[1,1,0]
	v_pk_fma_f32 v[68:69], v[68:69], v[164:165], v[48:49] op_sel_hi:[1,0,1]
	v_pk_mul_f32 v[180:181], v[180:181], s[62:63] op_sel_hi:[1,0]
	v_cndmask_b32_e64 v73, v73, v69, s[38:39]
	v_cndmask_b32_e64 v72, v72, v68, s[38:39]
	v_pk_fma_f32 v[68:69], v[66:67], s[6:7], v[138:139] op_sel_hi:[1,0,0]
	v_exp_f32_e32 v180, v180
	v_pk_fma_f32 v[68:69], v[66:67], v[68:69], s[26:27] op_sel_hi:[1,1,0]
	v_exp_f32_e32 v181, v181
	v_pk_fma_f32 v[68:69], v[66:67], v[68:69], s[30:31] op_sel_hi:[1,1,0]
	v_pk_fma_f32 v[68:69], v[66:67], v[68:69], s[40:41] op_sel_hi:[1,1,0]
	s_nop 0
	v_pk_mul_f32 v[66:67], v[66:67], v[68:69]
	v_pk_mul_f32 v[68:69], v[178:179], v[178:179]
	v_pk_mul_f32 v[66:67], v[180:181], v[66:67]
	v_pk_mul_f32 v[68:69], v[68:69], s[62:63] op_sel_hi:[1,0]
	v_max_f32_e32 v180, 0, v70
	v_max_f32_e32 v181, 0, v71
	v_fma_f32 v66, -|v70|, v66, v180
	v_fma_f32 v67, -|v71|, v67, v181
	v_fma_f32 v70, |v178|, s2, 1.0
	v_fma_f32 v71, |v179|, s2, 1.0
	v_rcp_f32_e32 v70, v70
	v_rcp_f32_e32 v71, v71
	v_exp_f32_e32 v68, v68
	v_exp_f32_e32 v69, v69
	v_pk_fma_f32 v[180:181], v[70:71], s[6:7], v[138:139] op_sel_hi:[1,0,0]
	s_nop 0
	v_pk_fma_f32 v[180:181], v[70:71], v[180:181], s[26:27] op_sel_hi:[1,1,0]
	s_nop 0
	v_pk_fma_f32 v[180:181], v[70:71], v[180:181], s[30:31] op_sel_hi:[1,1,0]
	s_nop 0
	v_pk_fma_f32 v[180:181], v[70:71], v[180:181], s[40:41] op_sel_hi:[1,1,0]
	s_nop 0
	v_pk_mul_f32 v[70:71], v[70:71], v[180:181]
	v_pk_mul_f32 v[180:181], v[166:167], v[166:167]
	v_pk_mul_f32 v[68:69], v[68:69], v[70:71]
	v_pk_mul_f32 v[180:181], v[180:181], s[62:63] op_sel_hi:[1,0]
	v_max_f32_e32 v70, 0, v178
	v_max_f32_e32 v71, 0, v179
	v_fma_f32 v68, -|v178|, v68, v70
	v_fma_f32 v69, -|v179|, v69, v71
	v_exp_f32_e32 v180, v180
	v_exp_f32_e32 v181, v181
	v_fma_f32 v70, |v166|, s2, 1.0
	v_fma_f32 v71, |v167|, s2, 1.0
	v_rcp_f32_e32 v70, v70
	v_rcp_f32_e32 v71, v71
	s_nop 0
	v_pk_fma_f32 v[178:179], v[70:71], s[6:7], v[138:139] op_sel_hi:[1,0,0]
	s_nop 0
	v_pk_fma_f32 v[178:179], v[70:71], v[178:179], s[26:27] op_sel_hi:[1,1,0]
	s_nop 0
	v_pk_fma_f32 v[178:179], v[70:71], v[178:179], s[30:31] op_sel_hi:[1,1,0]
	s_nop 0
	v_pk_fma_f32 v[178:179], v[70:71], v[178:179], s[40:41] op_sel_hi:[1,1,0]
	s_nop 0
	v_pk_mul_f32 v[70:71], v[70:71], v[178:179]
	v_pk_mul_f32 v[178:179], v[72:73], v[72:73]
	v_pk_mul_f32 v[70:71], v[180:181], v[70:71]
	v_pk_mul_f32 v[178:179], v[178:179], s[62:63] op_sel_hi:[1,0]
	v_max_f32_e32 v180, 0, v166
	v_max_f32_e32 v181, 0, v167
	v_fma_f32 v70, -|v166|, v70, v180
	v_fma_f32 v71, -|v167|, v71, v181
	v_fma_f32 v166, |v72|, s2, 1.0
	v_fma_f32 v167, |v73|, s2, 1.0
	v_rcp_f32_e32 v166, v166
	v_rcp_f32_e32 v167, v167
	v_exp_f32_e32 v178, v178
	v_exp_f32_e32 v179, v179
	v_pk_fma_f32 v[180:181], v[166:167], s[6:7], v[138:139] op_sel_hi:[1,0,0]
	s_nop 0
	v_pk_fma_f32 v[180:181], v[166:167], v[180:181], s[26:27] op_sel_hi:[1,1,0]
	s_nop 0
	v_pk_fma_f32 v[180:181], v[166:167], v[180:181], s[30:31] op_sel_hi:[1,1,0]
	s_nop 0
	v_pk_fma_f32 v[180:181], v[166:167], v[180:181], s[40:41] op_sel_hi:[1,1,0]
	s_nop 0
	v_pk_mul_f32 v[166:167], v[166:167], v[180:181]
	v_cvt_pk_bf16_f32 v180, v70, v71
	v_pk_mul_f32 v[166:167], v[178:179], v[166:167]
	s_nop 0
	v_max_f32_e32 v178, 0, v72
	v_max_f32_e32 v179, 0, v73
	v_fma_f32 v166, -|v72|, v166, v178
	v_fma_f32 v167, -|v73|, v167, v179
	s_nop 0
	v_mov_b32_e32 v72, v166
	v_cvt_pk_bf16_f32 v178, v66, v67
	s_nop 0
	v_mov_b32_e32 v73, v167
	v_cvt_pk_bf16_f32 v179, v68, v69
	v_cvt_pk_bf16_f32 v181, v72, v73
	global_store_dwordx4 v[162:163], v[178:181], off offset:256
	v_fmamk_f32 v162, v177, 0x3a800000, v202
	v_cmp_gt_f32_e32 vcc, s68, v162
	v_mul_f32_e32 v163, 0x4b800000, v162
	s_nop 0
	v_cndmask_b32_e32 v162, v162, v163, vcc
	v_rsq_f32_e32 v162, v162
	s_nop 0
	v_mul_f32_e32 v163, 0x45800000, v162
	v_cndmask_b32_e32 v162, v162, v163, vcc
	v_cndmask_b32_e64 v164, v177, v162, s[38:39]
	v_pk_fma_f32 v[166:167], v[62:63], v[34:35], v[164:165] op_sel_hi:[1,1,0]
	v_pk_fma_f32 v[62:63], v[62:63], v[164:165], v[34:35] op_sel_hi:[1,0,1]
	v_mad_i64_i32 v[162:163], s[0:1], s4, v176, 0
	v_cndmask_b32_e64 v62, v166, v62, s[38:39]
	v_cndmask_b32_e64 v63, v167, v63, s[38:39]
	v_pk_fma_f32 v[166:167], v[58:59], v[42:43], v[164:165] op_sel_hi:[1,1,0]
	v_pk_fma_f32 v[58:59], v[58:59], v[164:165], v[42:43] op_sel_hi:[1,0,1]
	v_pk_fma_f32 v[176:177], v[64:65], v[36:37], v[164:165] op_sel_hi:[1,1,0]
	v_cndmask_b32_e64 v166, v166, v58, s[38:39]
	v_cndmask_b32_e64 v167, v167, v59, s[38:39]
	v_fma_f32 v58, |v62|, s2, 1.0
	v_fma_f32 v59, |v63|, s2, 1.0
	v_pk_fma_f32 v[64:65], v[64:65], v[164:165], v[36:37] op_sel_hi:[1,0,1]
	v_rcp_f32_e32 v58, v58
	v_rcp_f32_e32 v59, v59
	v_cndmask_b32_e64 v177, v177, v65, s[38:39]
	v_cndmask_b32_e64 v176, v176, v64, s[38:39]
	v_pk_fma_f32 v[64:65], v[60:61], v[44:45], v[164:165] op_sel_hi:[1,1,0]
	v_pk_fma_f32 v[60:61], v[60:61], v[164:165], v[44:45] op_sel_hi:[1,0,1]
	v_pk_mul_f32 v[178:179], v[62:63], v[62:63]
	v_cndmask_b32_e64 v65, v65, v61, s[38:39]
	v_cndmask_b32_e64 v64, v64, v60, s[38:39]
	v_pk_fma_f32 v[60:61], v[58:59], s[6:7], v[138:139] op_sel_hi:[1,0,0]
	v_pk_mul_f32 v[178:179], v[178:179], s[62:63] op_sel_hi:[1,0]
	v_pk_fma_f32 v[60:61], v[58:59], v[60:61], s[26:27] op_sel_hi:[1,1,0]
	v_exp_f32_e32 v178, v178
	v_exp_f32_e32 v179, v179
	v_pk_fma_f32 v[60:61], v[58:59], v[60:61], s[30:31] op_sel_hi:[1,1,0]
	v_pk_fma_f32 v[60:61], v[58:59], v[60:61], s[40:41] op_sel_hi:[1,1,0]
	v_lshl_add_u64 v[162:163], v[162:163], 1, v[158:159]
	v_pk_mul_f32 v[58:59], v[58:59], v[60:61]
	v_pk_mul_f32 v[60:61], v[176:177], v[176:177]
	v_pk_mul_f32 v[58:59], v[178:179], v[58:59]
	v_pk_mul_f32 v[60:61], v[60:61], s[62:63] op_sel_hi:[1,0]
	v_max_f32_e32 v178, 0, v62
	v_max_f32_e32 v179, 0, v63
	v_fma_f32 v58, -|v62|, v58, v178
	v_fma_f32 v59, -|v63|, v59, v179
	v_fma_f32 v62, |v176|, s2, 1.0
	v_fma_f32 v63, |v177|, s2, 1.0
	v_rcp_f32_e32 v62, v62
	v_rcp_f32_e32 v63, v63
	v_exp_f32_e32 v60, v60
	v_exp_f32_e32 v61, v61
	v_pk_fma_f32 v[178:179], v[62:63], s[6:7], v[138:139] op_sel_hi:[1,0,0]
	s_nop 0
	v_pk_fma_f32 v[178:179], v[62:63], v[178:179], s[26:27] op_sel_hi:[1,1,0]
	s_nop 0
	v_pk_fma_f32 v[178:179], v[62:63], v[178:179], s[30:31] op_sel_hi:[1,1,0]
	s_nop 0
	v_pk_fma_f32 v[178:179], v[62:63], v[178:179], s[40:41] op_sel_hi:[1,1,0]
	s_nop 0
	v_pk_mul_f32 v[62:63], v[62:63], v[178:179]
	v_pk_mul_f32 v[178:179], v[166:167], v[166:167]
	v_pk_mul_f32 v[60:61], v[60:61], v[62:63]
	v_pk_mul_f32 v[178:179], v[178:179], s[62:63] op_sel_hi:[1,0]
	v_max_f32_e32 v62, 0, v176
	v_max_f32_e32 v63, 0, v177
	v_fma_f32 v60, -|v176|, v60, v62
	v_fma_f32 v61, -|v177|, v61, v63
	v_exp_f32_e32 v178, v178
	v_exp_f32_e32 v179, v179
	v_fma_f32 v62, |v166|, s2, 1.0
	v_fma_f32 v63, |v167|, s2, 1.0
	v_rcp_f32_e32 v62, v62
	v_rcp_f32_e32 v63, v63
	s_nop 0
	v_pk_fma_f32 v[176:177], v[62:63], s[6:7], v[138:139] op_sel_hi:[1,0,0]
	s_nop 0
	v_pk_fma_f32 v[176:177], v[62:63], v[176:177], s[26:27] op_sel_hi:[1,1,0]
	s_nop 0
	v_pk_fma_f32 v[176:177], v[62:63], v[176:177], s[30:31] op_sel_hi:[1,1,0]
	s_nop 0
	v_pk_fma_f32 v[176:177], v[62:63], v[176:177], s[40:41] op_sel_hi:[1,1,0]
	s_nop 0
	v_pk_mul_f32 v[62:63], v[62:63], v[176:177]
	v_pk_mul_f32 v[176:177], v[64:65], v[64:65]
	v_pk_mul_f32 v[62:63], v[178:179], v[62:63]
	v_pk_mul_f32 v[176:177], v[176:177], s[62:63] op_sel_hi:[1,0]
	v_max_f32_e32 v178, 0, v166
	v_max_f32_e32 v179, 0, v167
	v_fma_f32 v62, -|v166|, v62, v178
	v_fma_f32 v63, -|v167|, v63, v179
	v_fma_f32 v166, |v64|, s2, 1.0
	v_fma_f32 v167, |v65|, s2, 1.0
	v_rcp_f32_e32 v166, v166
	v_rcp_f32_e32 v167, v167
	v_exp_f32_e32 v176, v176
	v_exp_f32_e32 v177, v177
	v_pk_fma_f32 v[178:179], v[166:167], s[6:7], v[138:139] op_sel_hi:[1,0,0]
	s_nop 0
	v_pk_fma_f32 v[178:179], v[166:167], v[178:179], s[26:27] op_sel_hi:[1,1,0]
	s_nop 0
	v_pk_fma_f32 v[178:179], v[166:167], v[178:179], s[30:31] op_sel_hi:[1,1,0]
	s_nop 0
	v_pk_fma_f32 v[178:179], v[166:167], v[178:179], s[40:41] op_sel_hi:[1,1,0]
	s_nop 0
	v_pk_mul_f32 v[166:167], v[166:167], v[178:179]
	v_cvt_pk_bf16_f32 v178, v62, v63
	v_pk_mul_f32 v[166:167], v[176:177], v[166:167]
	s_nop 0
	v_max_f32_e32 v176, 0, v64
	v_max_f32_e32 v177, 0, v65
	v_fma_f32 v166, -|v64|, v166, v176
	v_fma_f32 v167, -|v65|, v167, v177
	s_nop 0
	v_mov_b32_e32 v64, v166
	v_cvt_pk_bf16_f32 v176, v58, v59
	s_nop 0
	v_mov_b32_e32 v65, v167
	v_pk_fma_f32 v[166:167], v[54:55], v[38:39], v[164:165] op_sel_hi:[1,1,0]
	v_pk_fma_f32 v[54:55], v[54:55], v[164:165], v[38:39] op_sel_hi:[1,0,1]
	v_cvt_pk_bf16_f32 v177, v60, v61
	v_cndmask_b32_e64 v54, v166, v54, s[38:39]
	v_cndmask_b32_e64 v55, v167, v55, s[38:39]
	v_pk_fma_f32 v[166:167], v[50:51], v[46:47], v[164:165] op_sel_hi:[1,1,0]
	v_pk_fma_f32 v[50:51], v[50:51], v[164:165], v[46:47] op_sel_hi:[1,0,1]
	v_cvt_pk_bf16_f32 v179, v64, v65
	v_cndmask_b32_e64 v166, v166, v50, s[38:39]
	v_cndmask_b32_e64 v167, v167, v51, s[38:39]
	v_fma_f32 v50, |v54|, s2, 1.0
	v_fma_f32 v51, |v55|, s2, 1.0
	global_store_dwordx4 v[162:163], v[176:179], off
	v_rcp_f32_e32 v50, v50
	v_rcp_f32_e32 v51, v51
	v_pk_fma_f32 v[176:177], v[56:57], v[40:41], v[164:165] op_sel_hi:[1,1,0]
	v_pk_fma_f32 v[56:57], v[56:57], v[164:165], v[40:41] op_sel_hi:[1,0,1]
	v_pk_mul_f32 v[178:179], v[54:55], v[54:55]
	v_cndmask_b32_e64 v177, v177, v57, s[38:39]
	v_cndmask_b32_e64 v176, v176, v56, s[38:39]
	v_pk_fma_f32 v[56:57], v[52:53], v[48:49], v[164:165] op_sel_hi:[1,1,0]
	v_pk_fma_f32 v[52:53], v[52:53], v[164:165], v[48:49] op_sel_hi:[1,0,1]
	v_pk_mul_f32 v[178:179], v[178:179], s[62:63] op_sel_hi:[1,0]
	v_cndmask_b32_e64 v57, v57, v53, s[38:39]
	v_cndmask_b32_e64 v56, v56, v52, s[38:39]
	v_pk_fma_f32 v[52:53], v[50:51], s[6:7], v[138:139] op_sel_hi:[1,0,0]
	v_exp_f32_e32 v178, v178
	v_pk_fma_f32 v[52:53], v[50:51], v[52:53], s[26:27] op_sel_hi:[1,1,0]
	v_exp_f32_e32 v179, v179
	v_pk_fma_f32 v[52:53], v[50:51], v[52:53], s[30:31] op_sel_hi:[1,1,0]
	v_pk_fma_f32 v[52:53], v[50:51], v[52:53], s[40:41] op_sel_hi:[1,1,0]
	s_nop 0
	v_pk_mul_f32 v[50:51], v[50:51], v[52:53]
	v_pk_mul_f32 v[52:53], v[176:177], v[176:177]
	v_pk_mul_f32 v[50:51], v[178:179], v[50:51]
	v_pk_mul_f32 v[52:53], v[52:53], s[62:63] op_sel_hi:[1,0]
	v_max_f32_e32 v178, 0, v54
	v_max_f32_e32 v179, 0, v55
	v_fma_f32 v50, -|v54|, v50, v178
	v_fma_f32 v51, -|v55|, v51, v179
	v_fma_f32 v54, |v176|, s2, 1.0
	v_fma_f32 v55, |v177|, s2, 1.0
	v_rcp_f32_e32 v54, v54
	v_rcp_f32_e32 v55, v55
	v_exp_f32_e32 v52, v52
	v_exp_f32_e32 v53, v53
	v_pk_fma_f32 v[178:179], v[54:55], s[6:7], v[138:139] op_sel_hi:[1,0,0]
	s_nop 0
	v_pk_fma_f32 v[178:179], v[54:55], v[178:179], s[26:27] op_sel_hi:[1,1,0]
	s_nop 0
	v_pk_fma_f32 v[178:179], v[54:55], v[178:179], s[30:31] op_sel_hi:[1,1,0]
	s_nop 0
	v_pk_fma_f32 v[178:179], v[54:55], v[178:179], s[40:41] op_sel_hi:[1,1,0]
	s_nop 0
	v_pk_mul_f32 v[54:55], v[54:55], v[178:179]
	v_pk_mul_f32 v[178:179], v[166:167], v[166:167]
	v_pk_mul_f32 v[52:53], v[52:53], v[54:55]
	v_pk_mul_f32 v[178:179], v[178:179], s[62:63] op_sel_hi:[1,0]
	v_max_f32_e32 v54, 0, v176
	v_max_f32_e32 v55, 0, v177
	v_fma_f32 v52, -|v176|, v52, v54
	v_fma_f32 v53, -|v177|, v53, v55
	v_exp_f32_e32 v178, v178
	v_exp_f32_e32 v179, v179
	v_fma_f32 v54, |v166|, s2, 1.0
	v_fma_f32 v55, |v167|, s2, 1.0
	v_rcp_f32_e32 v54, v54
	v_rcp_f32_e32 v55, v55
	s_nop 0
	v_pk_fma_f32 v[176:177], v[54:55], s[6:7], v[138:139] op_sel_hi:[1,0,0]
	s_nop 0
	v_pk_fma_f32 v[176:177], v[54:55], v[176:177], s[26:27] op_sel_hi:[1,1,0]
	s_nop 0
	v_pk_fma_f32 v[176:177], v[54:55], v[176:177], s[30:31] op_sel_hi:[1,1,0]
	s_nop 0
	v_pk_fma_f32 v[176:177], v[54:55], v[176:177], s[40:41] op_sel_hi:[1,1,0]
	s_nop 0
	v_pk_mul_f32 v[54:55], v[54:55], v[176:177]
	v_pk_mul_f32 v[176:177], v[56:57], v[56:57]
	v_pk_mul_f32 v[54:55], v[178:179], v[54:55]
	v_pk_mul_f32 v[176:177], v[176:177], s[62:63] op_sel_hi:[1,0]
	v_max_f32_e32 v178, 0, v166
	v_max_f32_e32 v179, 0, v167
	v_fma_f32 v54, -|v166|, v54, v178
	v_fma_f32 v55, -|v167|, v55, v179
	v_fma_f32 v166, |v56|, s2, 1.0
	v_fma_f32 v167, |v57|, s2, 1.0
	v_rcp_f32_e32 v166, v166
	v_rcp_f32_e32 v167, v167
	v_exp_f32_e32 v176, v176
	v_exp_f32_e32 v177, v177
	v_pk_fma_f32 v[178:179], v[166:167], s[6:7], v[138:139] op_sel_hi:[1,0,0]
	s_nop 0
	v_pk_fma_f32 v[178:179], v[166:167], v[178:179], s[26:27] op_sel_hi:[1,1,0]
	s_nop 0
	v_pk_fma_f32 v[178:179], v[166:167], v[178:179], s[30:31] op_sel_hi:[1,1,0]
	s_nop 0
	v_pk_fma_f32 v[178:179], v[166:167], v[178:179], s[40:41] op_sel_hi:[1,1,0]
	s_nop 0
	v_pk_mul_f32 v[166:167], v[166:167], v[178:179]
	v_cvt_pk_bf16_f32 v178, v54, v55
	v_pk_mul_f32 v[166:167], v[176:177], v[166:167]
	s_nop 0
	v_max_f32_e32 v176, 0, v56
	v_max_f32_e32 v177, 0, v57
	v_fma_f32 v166, -|v56|, v166, v176
	v_fma_f32 v167, -|v57|, v167, v177
	s_nop 0
	v_mov_b32_e32 v56, v166
	v_cvt_pk_bf16_f32 v176, v50, v51
	s_nop 0
	v_mov_b32_e32 v57, v167
	v_cvt_pk_bf16_f32 v177, v52, v53
	v_cvt_pk_bf16_f32 v179, v56, v57
	global_store_dwordx4 v[162:163], v[176:179], off offset:256
	v_fmamk_f32 v162, v175, 0x3a800000, v202
	v_cmp_gt_f32_e32 vcc, s68, v162
	v_mul_f32_e32 v163, 0x4b800000, v162
	s_nop 0
	v_cndmask_b32_e32 v162, v162, v163, vcc
	v_rsq_f32_e32 v162, v162
	s_nop 0
	v_mul_f32_e32 v163, 0x45800000, v162
	v_cndmask_b32_e32 v162, v162, v163, vcc
	v_cndmask_b32_e64 v164, v175, v162, s[38:39]
	v_pk_fma_f32 v[166:167], v[30:31], v[34:35], v[164:165] op_sel_hi:[1,1,0]
	v_pk_fma_f32 v[30:31], v[30:31], v[164:165], v[34:35] op_sel_hi:[1,0,1]
	v_mad_i64_i32 v[162:163], s[0:1], s4, v174, 0
	v_cndmask_b32_e64 v30, v166, v30, s[38:39]
	v_cndmask_b32_e64 v31, v167, v31, s[38:39]
	v_pk_fma_f32 v[166:167], v[26:27], v[42:43], v[164:165] op_sel_hi:[1,1,0]
	v_pk_fma_f32 v[26:27], v[26:27], v[164:165], v[42:43] op_sel_hi:[1,0,1]
	v_pk_fma_f32 v[174:175], v[32:33], v[36:37], v[164:165] op_sel_hi:[1,1,0]
	v_cndmask_b32_e64 v166, v166, v26, s[38:39]
	v_cndmask_b32_e64 v167, v167, v27, s[38:39]
	v_fma_f32 v26, |v30|, s2, 1.0
	v_fma_f32 v27, |v31|, s2, 1.0
	v_pk_fma_f32 v[32:33], v[32:33], v[164:165], v[36:37] op_sel_hi:[1,0,1]
	v_rcp_f32_e32 v26, v26
	v_rcp_f32_e32 v27, v27
	v_cndmask_b32_e64 v175, v175, v33, s[38:39]
	v_cndmask_b32_e64 v174, v174, v32, s[38:39]
	v_pk_fma_f32 v[32:33], v[28:29], v[44:45], v[164:165] op_sel_hi:[1,1,0]
	v_pk_fma_f32 v[28:29], v[28:29], v[164:165], v[44:45] op_sel_hi:[1,0,1]
	v_pk_mul_f32 v[176:177], v[30:31], v[30:31]
	v_cndmask_b32_e64 v33, v33, v29, s[38:39]
	v_cndmask_b32_e64 v32, v32, v28, s[38:39]
	v_pk_fma_f32 v[28:29], v[26:27], s[6:7], v[138:139] op_sel_hi:[1,0,0]
	v_pk_mul_f32 v[176:177], v[176:177], s[62:63] op_sel_hi:[1,0]
	v_pk_fma_f32 v[28:29], v[26:27], v[28:29], s[26:27] op_sel_hi:[1,1,0]
	v_exp_f32_e32 v176, v176
	v_exp_f32_e32 v177, v177
	v_pk_fma_f32 v[28:29], v[26:27], v[28:29], s[30:31] op_sel_hi:[1,1,0]
	v_pk_fma_f32 v[28:29], v[26:27], v[28:29], s[40:41] op_sel_hi:[1,1,0]
	v_lshl_add_u64 v[162:163], v[162:163], 1, v[158:159]
	v_pk_mul_f32 v[26:27], v[26:27], v[28:29]
	v_pk_mul_f32 v[28:29], v[174:175], v[174:175]
	v_pk_mul_f32 v[26:27], v[176:177], v[26:27]
	v_pk_mul_f32 v[28:29], v[28:29], s[62:63] op_sel_hi:[1,0]
	v_max_f32_e32 v176, 0, v30
	v_max_f32_e32 v177, 0, v31
	v_fma_f32 v26, -|v30|, v26, v176
	v_fma_f32 v27, -|v31|, v27, v177
	v_fma_f32 v30, |v174|, s2, 1.0
	v_fma_f32 v31, |v175|, s2, 1.0
	v_rcp_f32_e32 v30, v30
	v_rcp_f32_e32 v31, v31
	v_exp_f32_e32 v28, v28
	v_exp_f32_e32 v29, v29
	v_pk_fma_f32 v[176:177], v[30:31], s[6:7], v[138:139] op_sel_hi:[1,0,0]
	s_nop 0
	v_pk_fma_f32 v[176:177], v[30:31], v[176:177], s[26:27] op_sel_hi:[1,1,0]
	s_nop 0
	v_pk_fma_f32 v[176:177], v[30:31], v[176:177], s[30:31] op_sel_hi:[1,1,0]
	s_nop 0
	v_pk_fma_f32 v[176:177], v[30:31], v[176:177], s[40:41] op_sel_hi:[1,1,0]
	s_nop 0
	v_pk_mul_f32 v[30:31], v[30:31], v[176:177]
	v_pk_mul_f32 v[176:177], v[166:167], v[166:167]
	v_pk_mul_f32 v[28:29], v[28:29], v[30:31]
	v_pk_mul_f32 v[176:177], v[176:177], s[62:63] op_sel_hi:[1,0]
	v_max_f32_e32 v30, 0, v174
	v_max_f32_e32 v31, 0, v175
	v_fma_f32 v28, -|v174|, v28, v30
	v_fma_f32 v29, -|v175|, v29, v31
	v_exp_f32_e32 v176, v176
	v_exp_f32_e32 v177, v177
	v_fma_f32 v30, |v166|, s2, 1.0
	v_fma_f32 v31, |v167|, s2, 1.0
	v_rcp_f32_e32 v30, v30
	v_rcp_f32_e32 v31, v31
	s_nop 0
	v_pk_fma_f32 v[174:175], v[30:31], s[6:7], v[138:139] op_sel_hi:[1,0,0]
	s_nop 0
	v_pk_fma_f32 v[174:175], v[30:31], v[174:175], s[26:27] op_sel_hi:[1,1,0]
	s_nop 0
	v_pk_fma_f32 v[174:175], v[30:31], v[174:175], s[30:31] op_sel_hi:[1,1,0]
	s_nop 0
	v_pk_fma_f32 v[174:175], v[30:31], v[174:175], s[40:41] op_sel_hi:[1,1,0]
	s_nop 0
	v_pk_mul_f32 v[30:31], v[30:31], v[174:175]
	v_pk_mul_f32 v[174:175], v[32:33], v[32:33]
	v_pk_mul_f32 v[30:31], v[176:177], v[30:31]
	v_pk_mul_f32 v[174:175], v[174:175], s[62:63] op_sel_hi:[1,0]
	v_max_f32_e32 v176, 0, v166
	v_max_f32_e32 v177, 0, v167
	v_fma_f32 v30, -|v166|, v30, v176
	v_fma_f32 v31, -|v167|, v31, v177
	v_fma_f32 v166, |v32|, s2, 1.0
	v_fma_f32 v167, |v33|, s2, 1.0
	v_rcp_f32_e32 v166, v166
	v_rcp_f32_e32 v167, v167
	v_exp_f32_e32 v174, v174
	v_exp_f32_e32 v175, v175
	v_pk_fma_f32 v[176:177], v[166:167], s[6:7], v[138:139] op_sel_hi:[1,0,0]
	s_nop 0
	v_pk_fma_f32 v[176:177], v[166:167], v[176:177], s[26:27] op_sel_hi:[1,1,0]
	s_nop 0
	v_pk_fma_f32 v[176:177], v[166:167], v[176:177], s[30:31] op_sel_hi:[1,1,0]
	s_nop 0
	v_pk_fma_f32 v[176:177], v[166:167], v[176:177], s[40:41] op_sel_hi:[1,1,0]
	s_nop 0
	v_pk_mul_f32 v[166:167], v[166:167], v[176:177]
	v_cvt_pk_bf16_f32 v176, v30, v31
	v_pk_mul_f32 v[166:167], v[174:175], v[166:167]
	s_nop 0
	v_max_f32_e32 v174, 0, v32
	v_max_f32_e32 v175, 0, v33
	v_fma_f32 v166, -|v32|, v166, v174
	v_fma_f32 v167, -|v33|, v167, v175
	s_nop 0
	v_mov_b32_e32 v32, v166
	v_cvt_pk_bf16_f32 v174, v26, v27
	s_nop 0
	v_mov_b32_e32 v33, v167
	v_pk_fma_f32 v[166:167], v[22:23], v[38:39], v[164:165] op_sel_hi:[1,1,0]
	v_pk_fma_f32 v[22:23], v[22:23], v[164:165], v[38:39] op_sel_hi:[1,0,1]
	v_cvt_pk_bf16_f32 v175, v28, v29
	v_cndmask_b32_e64 v22, v166, v22, s[38:39]
	v_cndmask_b32_e64 v23, v167, v23, s[38:39]
	v_pk_fma_f32 v[166:167], v[18:19], v[46:47], v[164:165] op_sel_hi:[1,1,0]
	v_pk_fma_f32 v[18:19], v[18:19], v[164:165], v[46:47] op_sel_hi:[1,0,1]
	v_cvt_pk_bf16_f32 v177, v32, v33
	v_cndmask_b32_e64 v166, v166, v18, s[38:39]
	v_cndmask_b32_e64 v167, v167, v19, s[38:39]
	v_fma_f32 v18, |v22|, s2, 1.0
	v_fma_f32 v19, |v23|, s2, 1.0
	global_store_dwordx4 v[162:163], v[174:177], off
	v_rcp_f32_e32 v18, v18
	v_rcp_f32_e32 v19, v19
	v_pk_fma_f32 v[174:175], v[24:25], v[40:41], v[164:165] op_sel_hi:[1,1,0]
	v_pk_fma_f32 v[24:25], v[24:25], v[164:165], v[40:41] op_sel_hi:[1,0,1]
	v_pk_mul_f32 v[176:177], v[22:23], v[22:23]
	v_cndmask_b32_e64 v175, v175, v25, s[38:39]
	v_cndmask_b32_e64 v174, v174, v24, s[38:39]
	v_pk_fma_f32 v[24:25], v[20:21], v[48:49], v[164:165] op_sel_hi:[1,1,0]
	v_pk_fma_f32 v[20:21], v[20:21], v[164:165], v[48:49] op_sel_hi:[1,0,1]
	v_pk_mul_f32 v[176:177], v[176:177], s[62:63] op_sel_hi:[1,0]
	v_cndmask_b32_e64 v25, v25, v21, s[38:39]
	v_cndmask_b32_e64 v24, v24, v20, s[38:39]
	v_pk_fma_f32 v[20:21], v[18:19], s[6:7], v[138:139] op_sel_hi:[1,0,0]
	v_exp_f32_e32 v176, v176
	v_pk_fma_f32 v[20:21], v[18:19], v[20:21], s[26:27] op_sel_hi:[1,1,0]
	v_exp_f32_e32 v177, v177
	v_pk_fma_f32 v[20:21], v[18:19], v[20:21], s[30:31] op_sel_hi:[1,1,0]
	v_pk_fma_f32 v[20:21], v[18:19], v[20:21], s[40:41] op_sel_hi:[1,1,0]
	s_nop 0
	v_pk_mul_f32 v[18:19], v[18:19], v[20:21]
	v_pk_mul_f32 v[20:21], v[174:175], v[174:175]
	v_pk_mul_f32 v[18:19], v[176:177], v[18:19]
	v_pk_mul_f32 v[20:21], v[20:21], s[62:63] op_sel_hi:[1,0]
	v_max_f32_e32 v176, 0, v22
	v_max_f32_e32 v177, 0, v23
	v_fma_f32 v18, -|v22|, v18, v176
	v_fma_f32 v19, -|v23|, v19, v177
	v_fma_f32 v22, |v174|, s2, 1.0
	v_fma_f32 v23, |v175|, s2, 1.0
	v_rcp_f32_e32 v22, v22
	v_rcp_f32_e32 v23, v23
	v_exp_f32_e32 v20, v20
	v_exp_f32_e32 v21, v21
	v_pk_fma_f32 v[176:177], v[22:23], s[6:7], v[138:139] op_sel_hi:[1,0,0]
	s_nop 0
	v_pk_fma_f32 v[176:177], v[22:23], v[176:177], s[26:27] op_sel_hi:[1,1,0]
	s_nop 0
	v_pk_fma_f32 v[176:177], v[22:23], v[176:177], s[30:31] op_sel_hi:[1,1,0]
	s_nop 0
	v_pk_fma_f32 v[176:177], v[22:23], v[176:177], s[40:41] op_sel_hi:[1,1,0]
	s_nop 0
	v_pk_mul_f32 v[22:23], v[22:23], v[176:177]
	v_pk_mul_f32 v[176:177], v[166:167], v[166:167]
	v_pk_mul_f32 v[20:21], v[20:21], v[22:23]
	v_pk_mul_f32 v[176:177], v[176:177], s[62:63] op_sel_hi:[1,0]
	v_max_f32_e32 v22, 0, v174
	v_max_f32_e32 v23, 0, v175
	v_fma_f32 v20, -|v174|, v20, v22
	v_fma_f32 v21, -|v175|, v21, v23
	v_exp_f32_e32 v176, v176
	v_exp_f32_e32 v177, v177
	v_fma_f32 v22, |v166|, s2, 1.0
	v_fma_f32 v23, |v167|, s2, 1.0
	v_rcp_f32_e32 v22, v22
	v_rcp_f32_e32 v23, v23
	s_nop 0
	v_pk_fma_f32 v[174:175], v[22:23], s[6:7], v[138:139] op_sel_hi:[1,0,0]
	s_nop 0
	v_pk_fma_f32 v[174:175], v[22:23], v[174:175], s[26:27] op_sel_hi:[1,1,0]
	s_nop 0
	v_pk_fma_f32 v[174:175], v[22:23], v[174:175], s[30:31] op_sel_hi:[1,1,0]
	s_nop 0
	v_pk_fma_f32 v[174:175], v[22:23], v[174:175], s[40:41] op_sel_hi:[1,1,0]
	s_nop 0
	v_pk_mul_f32 v[22:23], v[22:23], v[174:175]
	v_pk_mul_f32 v[174:175], v[24:25], v[24:25]
	v_pk_mul_f32 v[22:23], v[176:177], v[22:23]
	v_pk_mul_f32 v[174:175], v[174:175], s[62:63] op_sel_hi:[1,0]
	v_max_f32_e32 v176, 0, v166
	v_max_f32_e32 v177, 0, v167
	v_fma_f32 v22, -|v166|, v22, v176
	v_fma_f32 v23, -|v167|, v23, v177
	v_fma_f32 v166, |v24|, s2, 1.0
	v_fma_f32 v167, |v25|, s2, 1.0
	v_rcp_f32_e32 v166, v166
	v_rcp_f32_e32 v167, v167
	v_exp_f32_e32 v174, v174
	v_exp_f32_e32 v175, v175
	v_pk_fma_f32 v[176:177], v[166:167], s[6:7], v[138:139] op_sel_hi:[1,0,0]
	s_nop 0
	v_pk_fma_f32 v[176:177], v[166:167], v[176:177], s[26:27] op_sel_hi:[1,1,0]
	s_nop 0
	v_pk_fma_f32 v[176:177], v[166:167], v[176:177], s[30:31] op_sel_hi:[1,1,0]
	s_nop 0
	v_pk_fma_f32 v[176:177], v[166:167], v[176:177], s[40:41] op_sel_hi:[1,1,0]
	s_nop 0
	v_pk_mul_f32 v[166:167], v[166:167], v[176:177]
	v_cvt_pk_bf16_f32 v176, v22, v23
	v_pk_mul_f32 v[166:167], v[174:175], v[166:167]
	s_nop 0
	v_max_f32_e32 v174, 0, v24
	v_max_f32_e32 v175, 0, v25
	v_fma_f32 v166, -|v24|, v166, v174
	v_fma_f32 v167, -|v25|, v167, v175
	s_nop 0
	v_mov_b32_e32 v24, v166
	v_cvt_pk_bf16_f32 v174, v18, v19
	s_nop 0
	v_mov_b32_e32 v25, v167
	v_cvt_pk_bf16_f32 v175, v20, v21
	v_cvt_pk_bf16_f32 v177, v24, v25
	global_store_dwordx4 v[162:163], v[174:177], off offset:256
	v_fmamk_f32 v162, v173, 0x3a800000, v202
	v_cmp_gt_f32_e32 vcc, s68, v162
	v_mul_f32_e32 v163, 0x4b800000, v162
	v_mad_i64_i32 v[166:167], s[0:1], s4, v172, 0
	v_cndmask_b32_e32 v162, v162, v163, vcc
	v_rsq_f32_e32 v162, v162
	v_lshl_add_u64 v[158:159], v[166:167], 1, v[158:159]
	v_mul_f32_e32 v163, 0x45800000, v162
	v_cndmask_b32_e32 v162, v162, v163, vcc
	v_cndmask_b32_e64 v162, v173, v162, s[38:39]
	v_pk_fma_f32 v[166:167], v[14:15], v[34:35], v[162:163] op_sel_hi:[1,1,0]
	v_pk_fma_f32 v[14:15], v[14:15], v[162:163], v[34:35] op_sel_hi:[1,0,1]
	v_pk_fma_f32 v[172:173], v[16:17], v[36:37], v[162:163] op_sel_hi:[1,1,0]
	v_pk_fma_f32 v[16:17], v[16:17], v[162:163], v[36:37] op_sel_hi:[1,0,1]
	v_cndmask_b32_e64 v14, v166, v14, s[38:39]
	v_cndmask_b32_e64 v15, v167, v15, s[38:39]
	v_pk_fma_f32 v[36:37], v[10:11], v[42:43], v[162:163] op_sel_hi:[1,1,0]
	v_pk_fma_f32 v[10:11], v[10:11], v[162:163], v[42:43] op_sel_hi:[1,0,1]
	v_cndmask_b32_e64 v35, v173, v17, s[38:39]
	v_cndmask_b32_e64 v36, v36, v10, s[38:39]
	v_cndmask_b32_e64 v37, v37, v11, s[38:39]
	v_fma_f32 v10, |v14|, s2, 1.0
	v_fma_f32 v11, |v15|, s2, 1.0
	v_cndmask_b32_e64 v34, v172, v16, s[38:39]
	v_rcp_f32_e32 v10, v10
	v_rcp_f32_e32 v11, v11
	v_pk_fma_f32 v[16:17], v[12:13], v[44:45], v[162:163] op_sel_hi:[1,1,0]
	v_pk_fma_f32 v[12:13], v[12:13], v[162:163], v[44:45] op_sel_hi:[1,0,1]
	v_pk_mul_f32 v[42:43], v[14:15], v[14:15]
	v_cndmask_b32_e64 v17, v17, v13, s[38:39]
	v_cndmask_b32_e64 v16, v16, v12, s[38:39]
	v_pk_fma_f32 v[12:13], v[10:11], s[6:7], v[138:139] op_sel_hi:[1,0,0]
	v_pk_mul_f32 v[42:43], v[42:43], s[62:63] op_sel_hi:[1,0]
	v_pk_fma_f32 v[12:13], v[10:11], v[12:13], s[26:27] op_sel_hi:[1,1,0]
	v_exp_f32_e32 v42, v42
	v_exp_f32_e32 v43, v43
	v_pk_fma_f32 v[12:13], v[10:11], v[12:13], s[30:31] op_sel_hi:[1,1,0]
	v_pk_fma_f32 v[12:13], v[10:11], v[12:13], s[40:41] op_sel_hi:[1,1,0]
	s_nop 0
	v_pk_mul_f32 v[10:11], v[10:11], v[12:13]
	v_pk_mul_f32 v[12:13], v[34:35], v[34:35]
	v_pk_mul_f32 v[10:11], v[42:43], v[10:11]
	v_pk_mul_f32 v[12:13], v[12:13], s[62:63] op_sel_hi:[1,0]
	v_max_f32_e32 v42, 0, v14
	v_max_f32_e32 v43, 0, v15
	v_fma_f32 v10, -|v14|, v10, v42
	v_fma_f32 v11, -|v15|, v11, v43
	v_fma_f32 v14, |v34|, s2, 1.0
	v_fma_f32 v15, |v35|, s2, 1.0
	v_rcp_f32_e32 v14, v14
	v_rcp_f32_e32 v15, v15
	v_exp_f32_e32 v12, v12
	v_exp_f32_e32 v13, v13
	v_pk_fma_f32 v[42:43], v[14:15], s[6:7], v[138:139] op_sel_hi:[1,0,0]
	s_nop 0
	v_pk_fma_f32 v[42:43], v[14:15], v[42:43], s[26:27] op_sel_hi:[1,1,0]
	s_nop 0
	v_pk_fma_f32 v[42:43], v[14:15], v[42:43], s[30:31] op_sel_hi:[1,1,0]
	s_nop 0
	v_pk_fma_f32 v[42:43], v[14:15], v[42:43], s[40:41] op_sel_hi:[1,1,0]
	s_nop 0
	v_pk_mul_f32 v[14:15], v[14:15], v[42:43]
	v_pk_mul_f32 v[42:43], v[36:37], v[36:37]
	v_pk_mul_f32 v[12:13], v[12:13], v[14:15]
	v_pk_mul_f32 v[42:43], v[42:43], s[62:63] op_sel_hi:[1,0]
	v_max_f32_e32 v14, 0, v34
	v_max_f32_e32 v15, 0, v35
	v_fma_f32 v12, -|v34|, v12, v14
	v_fma_f32 v13, -|v35|, v13, v15
	v_exp_f32_e32 v42, v42
	v_exp_f32_e32 v43, v43
	v_fma_f32 v14, |v36|, s2, 1.0
	v_fma_f32 v15, |v37|, s2, 1.0
	v_rcp_f32_e32 v14, v14
	v_rcp_f32_e32 v15, v15
	s_nop 0
	v_pk_fma_f32 v[34:35], v[14:15], s[6:7], v[138:139] op_sel_hi:[1,0,0]
	s_nop 0
	v_pk_fma_f32 v[34:35], v[14:15], v[34:35], s[26:27] op_sel_hi:[1,1,0]
	s_nop 0
	v_pk_fma_f32 v[34:35], v[14:15], v[34:35], s[30:31] op_sel_hi:[1,1,0]
	s_nop 0
	v_pk_fma_f32 v[34:35], v[14:15], v[34:35], s[40:41] op_sel_hi:[1,1,0]
	s_nop 0
	v_pk_mul_f32 v[14:15], v[14:15], v[34:35]
	v_pk_mul_f32 v[34:35], v[16:17], v[16:17]
	v_pk_mul_f32 v[14:15], v[42:43], v[14:15]
	v_pk_mul_f32 v[34:35], v[34:35], s[62:63] op_sel_hi:[1,0]
	v_max_f32_e32 v42, 0, v36
	v_max_f32_e32 v43, 0, v37
	v_fma_f32 v14, -|v36|, v14, v42
	v_fma_f32 v15, -|v37|, v15, v43
	v_fma_f32 v36, |v16|, s2, 1.0
	v_fma_f32 v37, |v17|, s2, 1.0
	v_rcp_f32_e32 v36, v36
	v_rcp_f32_e32 v37, v37
	v_exp_f32_e32 v34, v34
	v_exp_f32_e32 v35, v35
	v_pk_fma_f32 v[42:43], v[36:37], s[6:7], v[138:139] op_sel_hi:[1,0,0]
	s_nop 0
	v_pk_fma_f32 v[42:43], v[36:37], v[42:43], s[26:27] op_sel_hi:[1,1,0]
	s_nop 0
	v_pk_fma_f32 v[42:43], v[36:37], v[42:43], s[30:31] op_sel_hi:[1,1,0]
	s_nop 0
	v_pk_fma_f32 v[42:43], v[36:37], v[42:43], s[40:41] op_sel_hi:[1,1,0]
	s_nop 0
	v_pk_mul_f32 v[36:37], v[36:37], v[42:43]
	s_nop 0
	v_pk_mul_f32 v[34:35], v[34:35], v[36:37]
	s_nop 0
	v_max_f32_e32 v36, 0, v16
	v_max_f32_e32 v37, 0, v17
	v_fma_f32 v34, -|v16|, v34, v36
	v_fma_f32 v35, -|v17|, v35, v37
	s_nop 0
	v_mov_b32_e32 v16, v34
	v_cvt_pk_bf16_f32 v34, v10, v11
	v_cvt_pk_bf16_f32 v36, v14, v15
	v_mov_b32_e32 v17, v35
	v_cvt_pk_bf16_f32 v35, v12, v13
	v_cvt_pk_bf16_f32 v37, v16, v17
	global_store_dwordx4 v[158:159], v[34:37], off
	s_nop 1
	v_pk_fma_f32 v[34:35], v[6:7], v[38:39], v[162:163] op_sel_hi:[1,1,0]
	v_pk_fma_f32 v[36:37], v[8:9], v[40:41], v[162:163] op_sel_hi:[1,1,0]
	v_pk_fma_f32 v[6:7], v[6:7], v[162:163], v[38:39] op_sel_hi:[1,0,1]
	v_pk_fma_f32 v[8:9], v[8:9], v[162:163], v[40:41] op_sel_hi:[1,0,1]
	v_cndmask_b32_e64 v34, v34, v6, s[38:39]
	v_cndmask_b32_e64 v9, v37, v9, s[38:39]
	v_cndmask_b32_e64 v8, v36, v8, s[38:39]
	v_cndmask_b32_e64 v35, v35, v7, s[38:39]
	v_pk_fma_f32 v[36:37], v[2:3], v[46:47], v[162:163] op_sel_hi:[1,1,0]
	v_pk_fma_f32 v[2:3], v[2:3], v[162:163], v[46:47] op_sel_hi:[1,0,1]
	v_pk_fma_f32 v[6:7], v[4:5], v[48:49], v[162:163] op_sel_hi:[1,1,0]
	v_cndmask_b32_e64 v36, v36, v2, s[38:39]
	v_cndmask_b32_e64 v37, v37, v3, s[38:39]
	v_fma_f32 v2, |v34|, s2, 1.0
	v_fma_f32 v3, |v35|, s2, 1.0
	v_pk_fma_f32 v[4:5], v[4:5], v[162:163], v[48:49] op_sel_hi:[1,0,1]
	v_rcp_f32_e32 v2, v2
	v_rcp_f32_e32 v3, v3
	v_pk_mul_f32 v[38:39], v[34:35], v[34:35]
	v_cndmask_b32_e64 v7, v7, v5, s[38:39]
	v_cndmask_b32_e64 v6, v6, v4, s[38:39]
	v_pk_fma_f32 v[4:5], v[2:3], s[6:7], v[138:139] op_sel_hi:[1,0,0]
	v_pk_mul_f32 v[38:39], v[38:39], s[62:63] op_sel_hi:[1,0]
	v_pk_fma_f32 v[4:5], v[2:3], v[4:5], s[26:27] op_sel_hi:[1,1,0]
	v_exp_f32_e32 v38, v38
	v_exp_f32_e32 v39, v39
	v_pk_fma_f32 v[4:5], v[2:3], v[4:5], s[30:31] op_sel_hi:[1,1,0]
	v_pk_fma_f32 v[4:5], v[2:3], v[4:5], s[40:41] op_sel_hi:[1,1,0]
	s_nop 0
	v_pk_mul_f32 v[2:3], v[2:3], v[4:5]
	v_pk_mul_f32 v[4:5], v[8:9], v[8:9]
	v_pk_mul_f32 v[2:3], v[38:39], v[2:3]
	v_pk_mul_f32 v[4:5], v[4:5], s[62:63] op_sel_hi:[1,0]
	v_max_f32_e32 v38, 0, v34
	v_max_f32_e32 v39, 0, v35
	v_fma_f32 v2, -|v34|, v2, v38
	v_fma_f32 v3, -|v35|, v3, v39
	v_fma_f32 v34, |v8|, s2, 1.0
	v_fma_f32 v35, |v9|, s2, 1.0
	v_rcp_f32_e32 v34, v34
	v_rcp_f32_e32 v35, v35
	v_exp_f32_e32 v4, v4
	v_exp_f32_e32 v5, v5
	v_pk_fma_f32 v[38:39], v[34:35], s[6:7], v[138:139] op_sel_hi:[1,0,0]
	s_nop 0
	v_pk_fma_f32 v[38:39], v[34:35], v[38:39], s[26:27] op_sel_hi:[1,1,0]
	s_nop 0
	v_pk_fma_f32 v[38:39], v[34:35], v[38:39], s[30:31] op_sel_hi:[1,1,0]
	s_nop 0
	v_pk_fma_f32 v[38:39], v[34:35], v[38:39], s[40:41] op_sel_hi:[1,1,0]
	s_nop 0
	v_pk_mul_f32 v[34:35], v[34:35], v[38:39]
	v_pk_mul_f32 v[38:39], v[36:37], v[36:37]
	v_pk_mul_f32 v[4:5], v[4:5], v[34:35]
	v_pk_mul_f32 v[38:39], v[38:39], s[62:63] op_sel_hi:[1,0]
	v_max_f32_e32 v34, 0, v8
	v_max_f32_e32 v35, 0, v9
	v_fma_f32 v4, -|v8|, v4, v34
	v_fma_f32 v5, -|v9|, v5, v35
	v_fma_f32 v8, |v36|, s2, 1.0
	v_fma_f32 v9, |v37|, s2, 1.0
	v_rcp_f32_e32 v8, v8
	v_rcp_f32_e32 v9, v9
	v_exp_f32_e32 v38, v38
	v_exp_f32_e32 v39, v39
	v_pk_fma_f32 v[34:35], v[8:9], s[6:7], v[138:139] op_sel_hi:[1,0,0]
	s_nop 0
	v_pk_fma_f32 v[34:35], v[8:9], v[34:35], s[26:27] op_sel_hi:[1,1,0]
	s_nop 0
	v_pk_fma_f32 v[34:35], v[8:9], v[34:35], s[30:31] op_sel_hi:[1,1,0]
	s_nop 0
	v_pk_fma_f32 v[34:35], v[8:9], v[34:35], s[40:41] op_sel_hi:[1,1,0]
	s_nop 0
	v_pk_mul_f32 v[8:9], v[8:9], v[34:35]
	v_pk_mul_f32 v[34:35], v[6:7], v[6:7]
	v_pk_mul_f32 v[8:9], v[38:39], v[8:9]
	v_pk_mul_f32 v[34:35], v[34:35], s[62:63] op_sel_hi:[1,0]
	v_max_f32_e32 v38, 0, v36
	v_max_f32_e32 v39, 0, v37
	v_fma_f32 v8, -|v36|, v8, v38
	v_fma_f32 v9, -|v37|, v9, v39
	v_fma_f32 v36, |v6|, s2, 1.0
	v_fma_f32 v37, |v7|, s2, 1.0
	v_rcp_f32_e32 v36, v36
	v_rcp_f32_e32 v37, v37
	v_exp_f32_e32 v34, v34
	v_exp_f32_e32 v35, v35
	v_pk_fma_f32 v[38:39], v[36:37], s[6:7], v[138:139] op_sel_hi:[1,0,0]
	s_nop 0
	v_pk_fma_f32 v[38:39], v[36:37], v[38:39], s[26:27] op_sel_hi:[1,1,0]
	s_nop 0
	v_pk_fma_f32 v[38:39], v[36:37], v[38:39], s[30:31] op_sel_hi:[1,1,0]
	s_nop 0
	v_pk_fma_f32 v[38:39], v[36:37], v[38:39], s[40:41] op_sel_hi:[1,1,0]
	s_nop 0
	v_pk_mul_f32 v[36:37], v[36:37], v[38:39]
	v_cvt_pk_bf16_f32 v38, v8, v9
	v_pk_mul_f32 v[34:35], v[34:35], v[36:37]
	s_nop 0
	v_max_f32_e32 v36, 0, v6
	v_max_f32_e32 v37, 0, v7
	v_fma_f32 v34, -|v6|, v34, v36
	v_fma_f32 v35, -|v7|, v35, v37
	s_nop 0
	v_cvt_pk_bf16_f32 v36, v2, v3
	s_nop 0
	v_cvt_pk_bf16_f32 v37, v4, v5
	v_cvt_pk_bf16_f32 v39, v34, v35
	global_store_dwordx4 v[158:159], v[36:39], off offset:256
	s_and_b64 vcc, exec, s[36:37]
	s_movk_i32 s39, 0x6000
	s_cbranch_vccnz .LBB0_120
	v_pk_mul_f32 v[6:7], v[122:123], v[122:123]
	v_cmp_eq_u32_e32 vcc, 0, v171
	v_pk_fma_f32 v[6:7], v[140:141], v[140:141], v[6:7]
	s_nop 0
	v_pk_fma_f32 v[6:7], v[106:107], v[106:107], v[6:7]
	s_nop 0
	v_pk_fma_f32 v[6:7], v[90:91], v[90:91], v[6:7]
	s_nop 0
	v_pk_fma_f32 v[6:7], v[74:75], v[74:75], v[6:7]
	s_nop 0
	v_pk_fma_f32 v[6:7], v[58:59], v[58:59], v[6:7]
	s_nop 0
	v_pk_fma_f32 v[6:7], v[26:27], v[26:27], v[6:7]
	s_nop 0
	v_pk_fma_f32 v[26:27], v[10:11], v[10:11], v[6:7]
	s_nop 1
	v_add_f32_dpp v6, v26, v26 quad_perm:[1,0,3,2] row_mask:0xf bank_mask:0xf bound_ctrl:1
	s_nop 1
	v_add_f32_dpp v6, v6, v6 quad_perm:[2,3,0,1] row_mask:0xf bank_mask:0xf bound_ctrl:1
	s_nop 1
	v_add_f32_dpp v10, v6, v6 row_ror:4 row_mask:0xf bank_mask:0xf bound_ctrl:1
	v_lshl_add_u64 v[6:7], v[156:157], 2, s[44:45]
	s_nop 0
	v_mov_b32_dpp v11, v10 row_ror:8 row_mask:0xf bank_mask:0xf bound_ctrl:1
	s_and_saveexec_b64 s[0:1], vcc
	s_cbranch_execz .LBB0_89
	v_add_f32_e32 v10, v10, v11
	global_atomic_add_f32 v[6:7], v10, off

.LBB0_830:
	s_lshl_b32 s4, s30, 8
	v_mov_b32_e32 v66, v162
	v_mov_b32_e32 v67, v163
	s_add_i32 s4, s4, s25
	s_nop 0
	v_add_u32_e32 v158, s4, v66
	s_sub_i32 s4, s30, 32
	s_lshr_b32 s4, s4, 3
	s_mulk_i32 s4, 0x1600
	s_addk_i32 s4, 0x1600
	s_cmp_gt_i32 s30, 31
	s_cselect_b32 s30, s4, 0
	s_lshl_b64 s[4:5], s[30:31], 2
	s_add_u32 s6, s3, s4
	s_addc_u32 s7, s12, s5
	s_lshl_b32 s4, s2, 8
	s_ashr_i32 s5, s4, 31
	s_lshl_b64 s[4:5], s[4:5], 2
	s_add_u32 s4, s6, s4
	s_addc_u32 s5, s7, s5
	v_lshlrev_b32_e32 v156, 3, v67
	s_add_u32 s4, s4, s54
	s_addc_u32 s5, s5, 0
	v_ashrrev_i32_e32 v157, 31, v156
	v_ashrrev_i32_e32 v159, 31, v158
	v_lshl_add_u64 v[70:71], v[156:157], 2, s[4:5]
	v_lshl_add_u64 v[160:161], v[158:159], 2, s[42:43]
	global_load_dwordx4 v[74:77], v[70:71], off offset:16
	global_load_dwordx4 v[78:81], v[70:71], off
	global_load_dwordx4 v[66:69], v[70:71], off offset:528
	s_nop 0
	global_load_dwordx4 v[70:73], v[70:71], off offset:512
	s_lshl_b32 s2, s2, 7
	global_load_dword v157, v[160:161], off
	global_load_dword v179, v[160:161], off offset:64
	global_load_dword v177, v[160:161], off offset:128
	global_load_dword v175, v[160:161], off offset:192
	global_load_dword v173, v[160:161], off offset:512
	global_load_dword v171, v[160:161], off offset:576
	global_load_dword v169, v[160:161], off offset:640
	global_load_dword v167, v[160:161], off offset:704
	s_or_b32 s2, s2, s26
	v_add_u32_e32 v160, s2, v156
	v_ashrrev_i32_e32 v161, 31, v160
	s_movk_i32 s2, 0x1600
	v_add_u32_e32 v178, 16, v158
	v_add_u32_e32 v176, 32, v158
	v_add_u32_e32 v174, 48, v158
	v_add_u32_e32 v172, 0x80, v158
	v_add_u32_e32 v170, 0x90, v158
	v_add_u32_e32 v168, 0xa0, v158
	v_add_u32_e32 v166, 0xb0, v158
	s_waitcnt vmcnt(0)
	v_mul_f32_e32 v74, 0x3fb8aa3b, v74
	v_mul_f32_e32 v75, 0x3fb8aa3b, v75
	v_mul_f32_e32 v76, 0x3fb8aa3b, v76
	v_mul_f32_e32 v77, 0x3fb8aa3b, v77
	v_mul_f32_e32 v78, 0x3fb8aa3b, v78
	v_mul_f32_e32 v79, 0x3fb8aa3b, v79
	v_mul_f32_e32 v80, 0x3fb8aa3b, v80
	v_mul_f32_e32 v81, 0x3fb8aa3b, v81
	v_mul_f32_e32 v66, 0x3f317218, v66
	v_mul_f32_e32 v67, 0x3f317218, v67
	v_mul_f32_e32 v68, 0x3f317218, v68
	v_mul_f32_e32 v69, 0x3f317218, v69
	v_mul_f32_e32 v70, 0x3f317218, v70
	v_mul_f32_e32 v71, 0x3f317218, v71
	v_mul_f32_e32 v72, 0x3f317218, v72
	v_mul_f32_e32 v73, 0x3f317218, v73
	v_fmamk_f32 v156, v157, 0x3a800000, v202
	s_nop 0
	v_rsq_f32_e32 v156, v156
	s_nop 0
	v_mul_f32_e32 v184, 0x3fb8aa3b, v156
	v_mul_f32_e32 v186, 0x3f317218, v156
	v_mov_b64_e32 v[156:157], s[40:41]
	v_mad_i64_i32 v[182:183], s[4:5], v158, s2, v[156:157]
	v_lshlrev_b64 v[158:159], 1, v[160:161]
	v_pk_fma_f32 v[142:143], v[142:143], v[184:185], v[78:79] op_sel_hi:[1,0,1]
	v_lshl_add_u64 v[160:161], v[182:183], 0, v[158:159]
	v_pk_fma_f32 v[182:183], v[134:135], v[186:187], v[70:71] op_sel_hi:[1,0,1]
	v_pk_fma_f32 v[134:135], v[132:133], v[186:187], v[68:69] op_sel_hi:[1,0,1]
	v_pk_fma_f32 v[132:133], v[130:131], v[186:187], v[66:67] op_sel_hi:[1,0,1]
	v_exp_f32_e64 v130, -v142
	v_exp_f32_e64 v131, -v143
	v_pk_fma_f32 v[144:145], v[144:145], v[184:185], v[80:81] op_sel_hi:[1,0,1]
	v_pk_fma_f32 v[136:137], v[136:137], v[186:187], v[72:73] op_sel_hi:[1,0,1]
	v_add_f32_e32 v130, 1.0, v130
	v_add_f32_e32 v131, 1.0, v131
	v_rcp_f32_e32 v130, v130
	v_rcp_f32_e32 v131, v131
	v_pk_fma_f32 v[138:139], v[138:139], v[184:185], v[74:75] op_sel_hi:[1,0,1]
	v_pk_fma_f32 v[140:141], v[140:141], v[184:185], v[76:77] op_sel_hi:[1,0,1]
	v_pk_mul_f32 v[130:131], v[142:143], v[130:131]
	s_nop 0
	v_pk_mul_f32 v[130:131], v[182:183], v[130:131]
	s_nop 0
	v_cvt_pk_bf16_f32 v130, v130, v131
	v_exp_f32_e64 v131, -v144
	s_nop 0
	v_add_f32_e32 v131, 1.0, v131
	v_rcp_f32_e32 v142, v131
	v_exp_f32_e64 v131, -v145
	s_nop 0
	v_add_f32_e32 v131, 1.0, v131
	v_rcp_f32_e32 v143, v131
	s_nop 0
	v_pk_mul_f32 v[142:143], v[144:145], v[142:143]
	s_nop 0
	v_pk_mul_f32 v[136:137], v[136:137], v[142:143]
	s_nop 0
	v_cvt_pk_bf16_f32 v131, v136, v137
	v_exp_f32_e64 v136, -v138
	v_exp_f32_e64 v137, -v139
	v_add_f32_e32 v136, 1.0, v136
	v_add_f32_e32 v137, 1.0, v137
	v_rcp_f32_e32 v136, v136
	v_rcp_f32_e32 v137, v137
	s_nop 0
	v_pk_mul_f32 v[136:137], v[138:139], v[136:137]
	s_nop 0
	v_pk_mul_f32 v[132:133], v[132:133], v[136:137]
	s_nop 0
	v_cvt_pk_bf16_f32 v132, v132, v133
	v_exp_f32_e64 v133, -v140
	s_nop 0
	v_add_f32_e32 v133, 1.0, v133
	v_rcp_f32_e32 v136, v133
	v_exp_f32_e64 v133, -v141
	s_nop 0
	v_add_f32_e32 v133, 1.0, v133
	v_rcp_f32_e32 v137, v133
	s_nop 0
	v_pk_mul_f32 v[136:137], v[140:141], v[136:137]
	s_nop 0
	v_pk_mul_f32 v[134:135], v[134:135], v[136:137]
	s_nop 0
	v_cvt_pk_bf16_f32 v133, v134, v135
	global_store_dwordx4 v[160:161], v[130:133], off
	s_nop 1
	v_fmamk_f32 v130, v179, 0x3a800000, v202
	v_mad_i64_i32 v[132:133], s[4:5], v178, s2, v[156:157]
	v_rsq_f32_e32 v130, v130
	v_lshl_add_u64 v[132:133], v[132:133], 0, v[158:159]
	v_mul_f32_e32 v184, 0x3fb8aa3b, v130
	v_mul_f32_e32 v186, 0x3f317218, v130
	v_pk_fma_f32 v[126:127], v[126:127], v[184:185], v[78:79] op_sel_hi:[1,0,1]
	v_pk_fma_f32 v[134:135], v[116:117], v[186:187], v[68:69] op_sel_hi:[1,0,1]
	v_pk_fma_f32 v[116:117], v[114:115], v[186:187], v[66:67] op_sel_hi:[1,0,1]
	v_exp_f32_e64 v114, -v126
	v_exp_f32_e64 v115, -v127
	v_pk_fma_f32 v[118:119], v[118:119], v[186:187], v[70:71] op_sel_hi:[1,0,1]
	v_pk_fma_f32 v[128:129], v[128:129], v[184:185], v[80:81] op_sel_hi:[1,0,1]
	v_add_f32_e32 v114, 1.0, v114
	v_add_f32_e32 v115, 1.0, v115
	v_rcp_f32_e32 v114, v114
	v_rcp_f32_e32 v115, v115
	v_pk_fma_f32 v[120:121], v[120:121], v[186:187], v[72:73] op_sel_hi:[1,0,1]
	v_pk_fma_f32 v[122:123], v[122:123], v[184:185], v[74:75] op_sel_hi:[1,0,1]
	v_pk_fma_f32 v[124:125], v[124:125], v[184:185], v[76:77] op_sel_hi:[1,0,1]
	v_pk_mul_f32 v[114:115], v[126:127], v[114:115]
	s_nop 0
	v_pk_mul_f32 v[114:115], v[118:119], v[114:115]
	s_nop 0
	v_cvt_pk_bf16_f32 v114, v114, v115
	v_exp_f32_e64 v115, -v128
	s_nop 0
	v_add_f32_e32 v115, 1.0, v115
	v_rcp_f32_e32 v118, v115
	v_exp_f32_e64 v115, -v129
	s_nop 0
	v_add_f32_e32 v115, 1.0, v115
	v_rcp_f32_e32 v119, v115
	s_nop 0
	v_pk_mul_f32 v[118:119], v[128:129], v[118:119]
	s_nop 0
	v_pk_mul_f32 v[118:119], v[120:121], v[118:119]
	s_nop 0
	v_cvt_pk_bf16_f32 v115, v118, v119
	v_exp_f32_e64 v118, -v122
	v_exp_f32_e64 v119, -v123
	v_add_f32_e32 v118, 1.0, v118
	v_add_f32_e32 v119, 1.0, v119
	v_rcp_f32_e32 v118, v118
	v_rcp_f32_e32 v119, v119
	s_nop 0
	v_pk_mul_f32 v[118:119], v[122:123], v[118:119]
	s_nop 0
	v_pk_mul_f32 v[116:117], v[116:117], v[118:119]
	s_nop 0
	v_cvt_pk_bf16_f32 v116, v116, v117
	v_exp_f32_e64 v117, -v124
	s_nop 0
	v_add_f32_e32 v117, 1.0, v117
	v_rcp_f32_e32 v118, v117
	v_exp_f32_e64 v117, -v125
	s_nop 0
	v_add_f32_e32 v117, 1.0, v117
	v_rcp_f32_e32 v119, v117
	s_nop 0
	v_pk_mul_f32 v[118:119], v[124:125], v[118:119]
	s_nop 0
	v_pk_mul_f32 v[118:119], v[134:135], v[118:119]
	s_nop 0
	v_cvt_pk_bf16_f32 v117, v118, v119
	global_store_dwordx4 v[132:133], v[114:117], off
	s_nop 1
	v_fmamk_f32 v114, v177, 0x3a800000, v202
	v_mad_i64_i32 v[116:117], s[4:5], v176, s2, v[156:157]
	v_rsq_f32_e32 v114, v114
	v_lshl_add_u64 v[116:117], v[116:117], 0, v[158:159]
	v_mul_f32_e32 v184, 0x3fb8aa3b, v114
	v_mul_f32_e32 v186, 0x3f317218, v114
	v_pk_fma_f32 v[110:111], v[110:111], v[184:185], v[78:79] op_sel_hi:[1,0,1]
	v_pk_fma_f32 v[118:119], v[100:101], v[186:187], v[68:69] op_sel_hi:[1,0,1]
	v_pk_fma_f32 v[100:101], v[98:99], v[186:187], v[66:67] op_sel_hi:[1,0,1]
	v_exp_f32_e64 v98, -v110
	v_exp_f32_e64 v99, -v111
	v_pk_fma_f32 v[102:103], v[102:103], v[186:187], v[70:71] op_sel_hi:[1,0,1]
	v_pk_fma_f32 v[112:113], v[112:113], v[184:185], v[80:81] op_sel_hi:[1,0,1]
	v_add_f32_e32 v98, 1.0, v98
	v_add_f32_e32 v99, 1.0, v99
	v_rcp_f32_e32 v98, v98
	v_rcp_f32_e32 v99, v99
	v_pk_fma_f32 v[104:105], v[104:105], v[186:187], v[72:73] op_sel_hi:[1,0,1]
	v_pk_fma_f32 v[106:107], v[106:107], v[184:185], v[74:75] op_sel_hi:[1,0,1]
	v_pk_fma_f32 v[108:109], v[108:109], v[184:185], v[76:77] op_sel_hi:[1,0,1]
	v_pk_mul_f32 v[98:99], v[110:111], v[98:99]
	s_nop 0
	v_pk_mul_f32 v[98:99], v[102:103], v[98:99]
	s_nop 0
	v_cvt_pk_bf16_f32 v98, v98, v99
	v_exp_f32_e64 v99, -v112
	s_nop 0
	v_add_f32_e32 v99, 1.0, v99
	v_rcp_f32_e32 v102, v99
	v_exp_f32_e64 v99, -v113
	s_nop 0
	v_add_f32_e32 v99, 1.0, v99
	v_rcp_f32_e32 v103, v99
	s_nop 0
	v_pk_mul_f32 v[102:103], v[112:113], v[102:103]
	s_nop 0
	v_pk_mul_f32 v[102:103], v[104:105], v[102:103]
	s_nop 0
	v_cvt_pk_bf16_f32 v99, v102, v103
	v_exp_f32_e64 v102, -v106
	v_exp_f32_e64 v103, -v107
	v_add_f32_e32 v102, 1.0, v102
	v_add_f32_e32 v103, 1.0, v103
	v_rcp_f32_e32 v102, v102
	v_rcp_f32_e32 v103, v103
	s_nop 0
	v_pk_mul_f32 v[102:103], v[106:107], v[102:103]
	s_nop 0
	v_pk_mul_f32 v[100:101], v[100:101], v[102:103]
	s_nop 0
	v_cvt_pk_bf16_f32 v100, v100, v101
	v_exp_f32_e64 v101, -v108
	s_nop 0
	v_add_f32_e32 v101, 1.0, v101
	v_rcp_f32_e32 v102, v101
	v_exp_f32_e64 v101, -v109
	s_nop 0
	v_add_f32_e32 v101, 1.0, v101
	v_rcp_f32_e32 v103, v101
	s_nop 0
	v_pk_mul_f32 v[102:103], v[108:109], v[102:103]
	s_nop 0
	v_pk_mul_f32 v[102:103], v[118:119], v[102:103]
	s_nop 0
	v_cvt_pk_bf16_f32 v101, v102, v103
	global_store_dwordx4 v[116:117], v[98:101], off
	s_nop 1
	v_fmamk_f32 v98, v175, 0x3a800000, v202
	v_mad_i64_i32 v[100:101], s[4:5], v174, s2, v[156:157]
	v_rsq_f32_e32 v98, v98
	v_lshl_add_u64 v[100:101], v[100:101], 0, v[158:159]
	v_mul_f32_e32 v184, 0x3fb8aa3b, v98
	v_mul_f32_e32 v186, 0x3f317218, v98
	v_pk_fma_f32 v[94:95], v[94:95], v[184:185], v[78:79] op_sel_hi:[1,0,1]
	v_pk_fma_f32 v[102:103], v[84:85], v[186:187], v[68:69] op_sel_hi:[1,0,1]
	v_pk_fma_f32 v[84:85], v[82:83], v[186:187], v[66:67] op_sel_hi:[1,0,1]
	v_exp_f32_e64 v82, -v94
	v_exp_f32_e64 v83, -v95
	v_pk_fma_f32 v[86:87], v[86:87], v[186:187], v[70:71] op_sel_hi:[1,0,1]
	v_pk_fma_f32 v[96:97], v[96:97], v[184:185], v[80:81] op_sel_hi:[1,0,1]
	v_add_f32_e32 v82, 1.0, v82
	v_add_f32_e32 v83, 1.0, v83
	v_rcp_f32_e32 v82, v82
	v_rcp_f32_e32 v83, v83
	v_pk_fma_f32 v[88:89], v[88:89], v[186:187], v[72:73] op_sel_hi:[1,0,1]
	v_pk_fma_f32 v[90:91], v[90:91], v[184:185], v[74:75] op_sel_hi:[1,0,1]
	v_pk_fma_f32 v[92:93], v[92:93], v[184:185], v[76:77] op_sel_hi:[1,0,1]
	v_pk_mul_f32 v[82:83], v[94:95], v[82:83]
	s_nop 0
	v_pk_mul_f32 v[82:83], v[86:87], v[82:83]
	s_nop 0
	v_cvt_pk_bf16_f32 v82, v82, v83
	v_exp_f32_e64 v83, -v96
	s_nop 0
	v_add_f32_e32 v83, 1.0, v83
	v_rcp_f32_e32 v86, v83
	v_exp_f32_e64 v83, -v97
	s_nop 0
	v_add_f32_e32 v83, 1.0, v83
	v_rcp_f32_e32 v87, v83
	s_nop 0
	v_pk_mul_f32 v[86:87], v[96:97], v[86:87]
	s_nop 0
	v_pk_mul_f32 v[86:87], v[88:89], v[86:87]
	s_nop 0
	v_cvt_pk_bf16_f32 v83, v86, v87
	v_exp_f32_e64 v86, -v90
	v_exp_f32_e64 v87, -v91
	v_add_f32_e32 v86, 1.0, v86
	v_add_f32_e32 v87, 1.0, v87
	v_rcp_f32_e32 v86, v86
	v_rcp_f32_e32 v87, v87
	s_nop 0
	v_pk_mul_f32 v[86:87], v[90:91], v[86:87]
	s_nop 0
	v_pk_mul_f32 v[84:85], v[84:85], v[86:87]
	s_nop 0
	v_cvt_pk_bf16_f32 v84, v84, v85
	v_exp_f32_e64 v85, -v92
	s_nop 0
	v_add_f32_e32 v85, 1.0, v85
	v_rcp_f32_e32 v86, v85
	v_exp_f32_e64 v85, -v93
	s_nop 0
	v_add_f32_e32 v85, 1.0, v85
	v_rcp_f32_e32 v87, v85
	s_nop 0
	v_pk_mul_f32 v[86:87], v[92:93], v[86:87]
	s_nop 0
	v_pk_mul_f32 v[86:87], v[102:103], v[86:87]
	s_nop 0
	v_cvt_pk_bf16_f32 v85, v86, v87
	global_store_dwordx4 v[100:101], v[82:85], off
	s_nop 1
	v_fmamk_f32 v82, v173, 0x3a800000, v202
	v_mad_i64_i32 v[84:85], s[4:5], v172, s2, v[156:157]
	v_rsq_f32_e32 v82, v82
	v_lshl_add_u64 v[84:85], v[84:85], 0, v[158:159]
	v_mul_f32_e32 v184, 0x3fb8aa3b, v82
	v_mul_f32_e32 v186, 0x3f317218, v82
	v_pk_fma_f32 v[62:63], v[62:63], v[184:185], v[78:79] op_sel_hi:[1,0,1]
	v_pk_fma_f32 v[86:87], v[52:53], v[186:187], v[68:69] op_sel_hi:[1,0,1]
	v_pk_fma_f32 v[52:53], v[50:51], v[186:187], v[66:67] op_sel_hi:[1,0,1]
	v_exp_f32_e64 v50, -v62
	v_exp_f32_e64 v51, -v63
	v_pk_fma_f32 v[54:55], v[54:55], v[186:187], v[70:71] op_sel_hi:[1,0,1]
	v_pk_fma_f32 v[64:65], v[64:65], v[184:185], v[80:81] op_sel_hi:[1,0,1]
	v_add_f32_e32 v50, 1.0, v50
	v_add_f32_e32 v51, 1.0, v51
	v_rcp_f32_e32 v50, v50
	v_rcp_f32_e32 v51, v51
	v_pk_fma_f32 v[56:57], v[56:57], v[186:187], v[72:73] op_sel_hi:[1,0,1]
	v_pk_fma_f32 v[58:59], v[58:59], v[184:185], v[74:75] op_sel_hi:[1,0,1]
	v_pk_fma_f32 v[60:61], v[60:61], v[184:185], v[76:77] op_sel_hi:[1,0,1]
	v_pk_mul_f32 v[50:51], v[62:63], v[50:51]
	s_nop 0
	v_pk_mul_f32 v[50:51], v[54:55], v[50:51]
	s_nop 0
	v_cvt_pk_bf16_f32 v50, v50, v51
	v_exp_f32_e64 v51, -v64
	s_nop 0
	v_add_f32_e32 v51, 1.0, v51
	v_rcp_f32_e32 v54, v51
	v_exp_f32_e64 v51, -v65
	s_nop 0
	v_add_f32_e32 v51, 1.0, v51
	v_rcp_f32_e32 v55, v51
	s_nop 0
	v_pk_mul_f32 v[54:55], v[64:65], v[54:55]
	s_nop 0
	v_pk_mul_f32 v[54:55], v[56:57], v[54:55]
	s_nop 0
	v_cvt_pk_bf16_f32 v51, v54, v55
	v_exp_f32_e64 v54, -v58
	v_exp_f32_e64 v55, -v59
	v_add_f32_e32 v54, 1.0, v54
	v_add_f32_e32 v55, 1.0, v55
	v_rcp_f32_e32 v54, v54
	v_rcp_f32_e32 v55, v55
	s_nop 0
	v_pk_mul_f32 v[54:55], v[58:59], v[54:55]
	s_nop 0
	v_pk_mul_f32 v[52:53], v[52:53], v[54:55]
	s_nop 0
	v_cvt_pk_bf16_f32 v52, v52, v53
	v_exp_f32_e64 v53, -v60
	s_nop 0
	v_add_f32_e32 v53, 1.0, v53
	v_rcp_f32_e32 v54, v53
	v_exp_f32_e64 v53, -v61
	s_nop 0
	v_add_f32_e32 v53, 1.0, v53
	v_rcp_f32_e32 v55, v53
	s_nop 0
	v_pk_mul_f32 v[54:55], v[60:61], v[54:55]
	s_nop 0
	v_pk_mul_f32 v[54:55], v[86:87], v[54:55]
	s_nop 0
	v_cvt_pk_bf16_f32 v53, v54, v55
	global_store_dwordx4 v[84:85], v[50:53], off
	s_nop 1
	v_fmamk_f32 v50, v171, 0x3a800000, v202
	v_mad_i64_i32 v[52:53], s[4:5], v170, s2, v[156:157]
	v_rsq_f32_e32 v50, v50
	v_lshl_add_u64 v[52:53], v[52:53], 0, v[158:159]
	v_mul_f32_e32 v184, 0x3fb8aa3b, v50
	v_mul_f32_e32 v186, 0x3f317218, v50
	v_pk_fma_f32 v[46:47], v[46:47], v[184:185], v[78:79] op_sel_hi:[1,0,1]
	v_pk_fma_f32 v[54:55], v[36:37], v[186:187], v[68:69] op_sel_hi:[1,0,1]
	v_pk_fma_f32 v[36:37], v[34:35], v[186:187], v[66:67] op_sel_hi:[1,0,1]
	v_exp_f32_e64 v34, -v46
	v_exp_f32_e64 v35, -v47
	v_pk_fma_f32 v[38:39], v[38:39], v[186:187], v[70:71] op_sel_hi:[1,0,1]
	v_pk_fma_f32 v[48:49], v[48:49], v[184:185], v[80:81] op_sel_hi:[1,0,1]
	v_add_f32_e32 v34, 1.0, v34
	v_add_f32_e32 v35, 1.0, v35
	v_rcp_f32_e32 v34, v34
	v_rcp_f32_e32 v35, v35
	v_pk_fma_f32 v[40:41], v[40:41], v[186:187], v[72:73] op_sel_hi:[1,0,1]
	v_pk_fma_f32 v[42:43], v[42:43], v[184:185], v[74:75] op_sel_hi:[1,0,1]
	v_pk_fma_f32 v[44:45], v[44:45], v[184:185], v[76:77] op_sel_hi:[1,0,1]
	v_pk_mul_f32 v[34:35], v[46:47], v[34:35]
	s_nop 0
	v_pk_mul_f32 v[34:35], v[38:39], v[34:35]
	s_nop 0
	v_cvt_pk_bf16_f32 v34, v34, v35
	v_exp_f32_e64 v35, -v48
	s_nop 0
	v_add_f32_e32 v35, 1.0, v35
	v_rcp_f32_e32 v38, v35
	v_exp_f32_e64 v35, -v49
	s_nop 0
	v_add_f32_e32 v35, 1.0, v35
	v_rcp_f32_e32 v39, v35
	s_nop 0
	v_pk_mul_f32 v[38:39], v[48:49], v[38:39]
	s_nop 0
	v_pk_mul_f32 v[38:39], v[40:41], v[38:39]
	s_nop 0
	v_cvt_pk_bf16_f32 v35, v38, v39
	v_exp_f32_e64 v38, -v42
	v_exp_f32_e64 v39, -v43
	v_add_f32_e32 v38, 1.0, v38
	v_add_f32_e32 v39, 1.0, v39
	v_rcp_f32_e32 v38, v38
	v_rcp_f32_e32 v39, v39
	s_nop 0
	v_pk_mul_f32 v[38:39], v[42:43], v[38:39]
	s_nop 0
	v_pk_mul_f32 v[36:37], v[36:37], v[38:39]
	s_nop 0
	v_cvt_pk_bf16_f32 v36, v36, v37
	v_exp_f32_e64 v37, -v44
	s_nop 0
	v_add_f32_e32 v37, 1.0, v37
	v_rcp_f32_e32 v38, v37
	v_exp_f32_e64 v37, -v45
	s_nop 0
	v_add_f32_e32 v37, 1.0, v37
	v_rcp_f32_e32 v39, v37
	s_nop 0
	v_pk_mul_f32 v[38:39], v[44:45], v[38:39]
	s_nop 0
	v_pk_mul_f32 v[38:39], v[54:55], v[38:39]
	s_nop 0
	v_cvt_pk_bf16_f32 v37, v38, v39
	global_store_dwordx4 v[52:53], v[34:37], off
	s_nop 1
	v_fmamk_f32 v34, v169, 0x3a800000, v202
	v_mad_i64_i32 v[36:37], s[4:5], v168, s2, v[156:157]
	v_rsq_f32_e32 v34, v34
	v_lshl_add_u64 v[36:37], v[36:37], 0, v[158:159]
	v_mul_f32_e32 v184, 0x3fb8aa3b, v34
	v_mul_f32_e32 v186, 0x3f317218, v34
	v_pk_fma_f32 v[30:31], v[30:31], v[184:185], v[78:79] op_sel_hi:[1,0,1]
	v_pk_fma_f32 v[38:39], v[20:21], v[186:187], v[68:69] op_sel_hi:[1,0,1]
	v_pk_fma_f32 v[20:21], v[18:19], v[186:187], v[66:67] op_sel_hi:[1,0,1]
	v_exp_f32_e64 v18, -v30
	v_exp_f32_e64 v19, -v31
	v_pk_fma_f32 v[22:23], v[22:23], v[186:187], v[70:71] op_sel_hi:[1,0,1]
	v_pk_fma_f32 v[32:33], v[32:33], v[184:185], v[80:81] op_sel_hi:[1,0,1]
	v_add_f32_e32 v18, 1.0, v18
	v_add_f32_e32 v19, 1.0, v19
	v_rcp_f32_e32 v18, v18
	v_rcp_f32_e32 v19, v19
	v_pk_fma_f32 v[24:25], v[24:25], v[186:187], v[72:73] op_sel_hi:[1,0,1]
	v_pk_fma_f32 v[26:27], v[26:27], v[184:185], v[74:75] op_sel_hi:[1,0,1]
	v_pk_fma_f32 v[28:29], v[28:29], v[184:185], v[76:77] op_sel_hi:[1,0,1]
	v_pk_mul_f32 v[18:19], v[30:31], v[18:19]
	s_nop 0
	v_pk_mul_f32 v[18:19], v[22:23], v[18:19]
	s_nop 0
	v_cvt_pk_bf16_f32 v18, v18, v19
	v_exp_f32_e64 v19, -v32
	s_nop 0
	v_add_f32_e32 v19, 1.0, v19
	v_rcp_f32_e32 v22, v19
	v_exp_f32_e64 v19, -v33
	s_nop 0
	v_add_f32_e32 v19, 1.0, v19
	v_rcp_f32_e32 v23, v19
	s_nop 0
	v_pk_mul_f32 v[22:23], v[32:33], v[22:23]
	s_nop 0
	v_pk_mul_f32 v[22:23], v[24:25], v[22:23]
	s_nop 0
	v_cvt_pk_bf16_f32 v19, v22, v23
	v_exp_f32_e64 v22, -v26
	v_exp_f32_e64 v23, -v27
	v_add_f32_e32 v22, 1.0, v22
	v_add_f32_e32 v23, 1.0, v23
	v_rcp_f32_e32 v22, v22
	v_rcp_f32_e32 v23, v23
	s_nop 0
	v_pk_mul_f32 v[22:23], v[26:27], v[22:23]
	s_nop 0
	v_pk_mul_f32 v[20:21], v[20:21], v[22:23]
	s_nop 0
	v_cvt_pk_bf16_f32 v20, v20, v21
	v_exp_f32_e64 v21, -v28
	s_nop 0
	v_add_f32_e32 v21, 1.0, v21
	v_rcp_f32_e32 v22, v21
	v_exp_f32_e64 v21, -v29
	s_nop 0
	v_add_f32_e32 v21, 1.0, v21
	v_rcp_f32_e32 v23, v21
	s_nop 0
	v_pk_mul_f32 v[22:23], v[28:29], v[22:23]
	s_nop 0
	v_pk_mul_f32 v[22:23], v[38:39], v[22:23]
	s_nop 0
	v_cvt_pk_bf16_f32 v21, v22, v23
	global_store_dwordx4 v[36:37], v[18:21], off
	s_nop 1
	v_fmamk_f32 v18, v167, 0x3a800000, v202
	v_mad_i64_i32 v[20:21], s[4:5], v166, s2, v[156:157]
	v_rsq_f32_e32 v18, v18
	v_lshl_add_u64 v[20:21], v[20:21], 0, v[158:159]
	v_mul_f32_e32 v184, 0x3fb8aa3b, v18
	v_mul_f32_e32 v186, 0x3f317218, v18
	v_pk_fma_f32 v[14:15], v[14:15], v[184:185], v[78:79] op_sel_hi:[1,0,1]
	v_pk_fma_f32 v[22:23], v[4:5], v[186:187], v[68:69] op_sel_hi:[1,0,1]
	v_pk_fma_f32 v[4:5], v[2:3], v[186:187], v[66:67] op_sel_hi:[1,0,1]
	v_exp_f32_e64 v2, -v14
	v_exp_f32_e64 v3, -v15
	v_pk_fma_f32 v[6:7], v[6:7], v[186:187], v[70:71] op_sel_hi:[1,0,1]
	v_pk_fma_f32 v[16:17], v[16:17], v[184:185], v[80:81] op_sel_hi:[1,0,1]
	v_add_f32_e32 v2, 1.0, v2
	v_add_f32_e32 v3, 1.0, v3
	v_rcp_f32_e32 v2, v2
	v_rcp_f32_e32 v3, v3
	v_pk_fma_f32 v[8:9], v[8:9], v[186:187], v[72:73] op_sel_hi:[1,0,1]
	v_pk_fma_f32 v[10:11], v[10:11], v[184:185], v[74:75] op_sel_hi:[1,0,1]
	v_pk_fma_f32 v[12:13], v[12:13], v[184:185], v[76:77] op_sel_hi:[1,0,1]
	v_pk_mul_f32 v[2:3], v[14:15], v[2:3]
	s_nop 0
	v_pk_mul_f32 v[2:3], v[6:7], v[2:3]
	s_nop 0
	v_cvt_pk_bf16_f32 v2, v2, v3
	v_exp_f32_e64 v3, -v16
	s_nop 0
	v_add_f32_e32 v3, 1.0, v3
	v_rcp_f32_e32 v6, v3
	v_exp_f32_e64 v3, -v17
	s_nop 0
	v_add_f32_e32 v3, 1.0, v3
	v_rcp_f32_e32 v7, v3
	s_nop 0
	v_pk_mul_f32 v[6:7], v[16:17], v[6:7]
	s_nop 0
	v_pk_mul_f32 v[6:7], v[8:9], v[6:7]
	s_nop 0
	v_cvt_pk_bf16_f32 v3, v6, v7
	v_exp_f32_e64 v6, -v10
	v_exp_f32_e64 v7, -v11
	v_add_f32_e32 v6, 1.0, v6
	v_add_f32_e32 v7, 1.0, v7
	v_rcp_f32_e32 v6, v6
	v_rcp_f32_e32 v7, v7
	s_nop 0
	v_pk_mul_f32 v[6:7], v[10:11], v[6:7]
	s_nop 0
	v_pk_mul_f32 v[4:5], v[4:5], v[6:7]
	s_nop 0
	v_cvt_pk_bf16_f32 v4, v4, v5
	v_exp_f32_e64 v5, -v12
	s_nop 0
	v_add_f32_e32 v5, 1.0, v5
	v_rcp_f32_e32 v6, v5
	v_exp_f32_e64 v5, -v13
	s_nop 0
	v_add_f32_e32 v5, 1.0, v5
	v_rcp_f32_e32 v7, v5
	s_nop 0
	v_pk_mul_f32 v[6:7], v[12:13], v[6:7]
	s_nop 0
	v_pk_mul_f32 v[6:7], v[22:23], v[6:7]
	s_nop 0
	v_cvt_pk_bf16_f32 v5, v6, v7
	global_store_dwordx4 v[20:21], v[2:5], off
	s_andn2_b64 vcc, exec, s[34:35]
	s_mov_b64 s[4:5], -1
	s_cbranch_vccnz .LBB0_821
	s_andn2_b64 vcc, exec, s[38:39]
	s_cbranch_vccnz .LBB0_820
	s_barrier
	s_branch .LBB0_820
